# MLA attention loop: K/V fragment LDS reads kept in flight (ring buffers, counted lgkm waits), softmax cross-row max via v_permlane16/32_swap instead of ds_bpermute
# speedup vs baseline: 1.0013x; 1.0013x over previous
; #define LAS __attribute__((address_space(3)))
; template <int DQK, int D1, int DV, bool MLA, int NQ>
; DEVINL void attn_block(LAS unsigned char* lds, const bf16_t* q, int ldq, const bf16_t* k1, int ld1, const bf16_t* k2, int ld2,
;                        const bf16_t* vt, int ldv, bf16_t* o, int ldo, int nt, int qtile0, const f32x2* cs, float sc) {
;     ...
;         for (int i = 0; i < NC1; ++i) { const int c = tid + i * 512, row = c / CPR1, cc = c % CPR1; r1[i] = *(const u32x4*)(k1 + (size_t)(key0 + row) * ld1 + cc * 8); }
;         if (D2 > 0) { const int row = tid >> 3, cc = tid & 7; r2 = *(const u32x4*)(k2 + (size_t)(key0 + row) * ld2 + cc * 8); }
; #pragma unroll
;         for (int i = 0; i < NCV; ++i) { const int c = tid + i * 512, row = c >> 3, cc = c & 7; rv[i] = *(const u32x4*)(vt + (size_t)row * ldv + key0 + cc * 8); }
;     ...
;     for (int j = 0; j < nt; ++j) {
;         LAS unsigned char* cb = lds + (j & 1) * BUF;
;         if (j + 1 < nt) gload((j + 1) * 64);
;         if (j <= jmax) {
;             f32x4 s[NQ][4];
; #pragma unroll
;             for (int kb = 0; kb < 4; ++kb) {
; #pragma unroll
;                 for (int qi = 0; qi < NQ; ++qi) s[qi][kb] = (f32x4){0.f, 0.f, 0.f, 0.f};
; #pragma unroll
;                 for (int ks = 0; ks < NKS; ++ks) { const bf16x8 a = *(const LAS bf16x8*)(cb + (kb * 16 + fr) * KS + ks * 64 + fq * 16);
; #pragma unroll
;                     for (int qi = 0; qi < NQ; ++qi) s[qi][kb] = __builtin_amdgcn_mfma_f32_16x16x32_bf16(a, qf[qi][ks], s[qi][kb], 0, 0, 0); } }
.LBB0_911:
	v_lshl_add_u64 v[108:109], s[20:21], 0, v[180:181]
	v_lshl_add_u64 v[110:111], s[20:21], 0, v[178:179]
	v_lshl_add_u64 v[116:117], s[20:21], 0, v[176:177]
	v_lshl_add_u64 v[118:119], s[20:21], 0, v[172:173]
	v_lshl_add_u64 v[120:121], s[20:21], 0, v[174:175]
	global_load_dwordx4 v[112:115], v[108:109], off
	s_nop 0
	global_load_dwordx4 v[108:111], v[110:111], off
	s_nop 0
	global_load_dwordx4 v[124:127], v[116:117], off
	s_nop 0
	global_load_dwordx4 v[116:119], v[118:119], off
	v_cmp_le_i32_e32 vcc, s65, v219
	global_load_dwordx4 v[120:123], v[120:121], off
	s_and_saveexec_b64 s[6:7], vcc
	s_cbranch_execz .LBB0_910
	s_bitcmp1_b32 s65, 0
	s_cselect_b32 s2, 0xac00, 0
	s_add_i32 s66, s2, 16
	v_add3_u32 v145, s66, v168, v171
	ds_read_b128 v[184:187], v145 offset:0
	ds_read_b128 v[188:191], v145 offset:64
	ds_read_b128 v[192:195], v145 offset:128
	ds_read_b128 v[196:199], v145 offset:192
	ds_read_b128 v[206:209], v145 offset:256
	ds_read_b128 v[230:233], v145 offset:320
	s_waitcnt vmcnt(5)
	s_waitcnt lgkmcnt(5)
	v_mfma_f32_16x16x32_bf16 v[136:139], v[184:187], v[36:39], 0
	v_mfma_f32_16x16x32_bf16 v[132:135], v[184:187], v[72:75], 0
	ds_read_b128 v[234:237], v145 offset:6400
	s_waitcnt lgkmcnt(5)
	v_mfma_f32_16x16x32_bf16 v[136:139], v[188:191], v[32:35], v[136:139]
	v_mfma_f32_16x16x32_bf16 v[132:135], v[188:191], v[64:67], v[132:135]
	ds_read_b128 v[238:241], v145 offset:6464
	s_waitcnt lgkmcnt(5)
	v_mfma_f32_16x16x32_bf16 v[136:139], v[192:195], v[28:31], v[136:139]
	v_mfma_f32_16x16x32_bf16 v[132:135], v[192:195], v[60:63], v[132:135]
	ds_read_b128 v[184:187], v145 offset:6528
	s_waitcnt lgkmcnt(5)
	v_mfma_f32_16x16x32_bf16 v[136:139], v[196:199], v[24:27], v[136:139]
	v_mfma_f32_16x16x32_bf16 v[132:135], v[196:199], v[56:59], v[132:135]
	ds_read_b128 v[188:191], v145 offset:6592
	s_waitcnt lgkmcnt(5)
	v_mfma_f32_16x16x32_bf16 v[136:139], v[206:209], v[40:43], v[136:139]
	v_mfma_f32_16x16x32_bf16 v[132:135], v[206:209], v[76:79], v[132:135]
	ds_read_b128 v[192:195], v145 offset:6656
	s_waitcnt lgkmcnt(5)
	v_mfma_f32_16x16x32_bf16 v[136:139], v[230:233], v[52:55], v[136:139]
	v_mfma_f32_16x16x32_bf16 v[132:135], v[230:233], v[68:71], v[132:135]
	ds_read_b128 v[196:199], v145 offset:6720
	s_waitcnt lgkmcnt(5)
	v_mfma_f32_16x16x32_bf16 v[140:143], v[234:237], v[36:39], 0
	v_mfma_f32_16x16x32_bf16 v[148:151], v[234:237], v[72:75], 0
	ds_read_b128 v[206:209], v145 offset:12800
	s_waitcnt lgkmcnt(5)
	v_mfma_f32_16x16x32_bf16 v[140:143], v[238:241], v[32:35], v[140:143]
	v_mfma_f32_16x16x32_bf16 v[148:151], v[238:241], v[64:67], v[148:151]
	ds_read_b128 v[230:233], v145 offset:12864
	s_waitcnt lgkmcnt(5)
	v_mfma_f32_16x16x32_bf16 v[140:143], v[184:187], v[28:31], v[140:143]
	v_mfma_f32_16x16x32_bf16 v[148:151], v[184:187], v[60:63], v[148:151]
	ds_read_b128 v[234:237], v145 offset:12928
	s_waitcnt lgkmcnt(5)
	v_mfma_f32_16x16x32_bf16 v[140:143], v[188:191], v[24:27], v[140:143]
	v_mfma_f32_16x16x32_bf16 v[148:151], v[188:191], v[56:59], v[148:151]
	ds_read_b128 v[238:241], v145 offset:12992
	s_waitcnt lgkmcnt(5)
	v_mfma_f32_16x16x32_bf16 v[140:143], v[192:195], v[40:43], v[140:143]
	v_mfma_f32_16x16x32_bf16 v[148:151], v[192:195], v[76:79], v[148:151]
	ds_read_b128 v[184:187], v145 offset:13056
	s_waitcnt lgkmcnt(5)
	v_mfma_f32_16x16x32_bf16 v[140:143], v[196:199], v[52:55], v[140:143]
	v_mfma_f32_16x16x32_bf16 v[148:151], v[196:199], v[68:71], v[148:151]
	ds_read_b128 v[188:191], v145 offset:13120
	s_waitcnt lgkmcnt(5)
	v_mfma_f32_16x16x32_bf16 v[202:205], v[206:209], v[36:39], 0
	v_mfma_f32_16x16x32_bf16 v[152:155], v[206:209], v[72:75], 0
	ds_read_b128 v[192:195], v145 offset:19200
	s_waitcnt lgkmcnt(5)
	v_mfma_f32_16x16x32_bf16 v[202:205], v[230:233], v[32:35], v[202:205]
	v_mfma_f32_16x16x32_bf16 v[152:155], v[230:233], v[64:67], v[152:155]
	ds_read_b128 v[196:199], v145 offset:19264
	s_waitcnt lgkmcnt(5)
	v_mfma_f32_16x16x32_bf16 v[202:205], v[234:237], v[28:31], v[202:205]
	v_mfma_f32_16x16x32_bf16 v[152:155], v[234:237], v[60:63], v[152:155]
	ds_read_b128 v[206:209], v145 offset:19328
	s_waitcnt lgkmcnt(5)
	v_mfma_f32_16x16x32_bf16 v[202:205], v[238:241], v[24:27], v[202:205]
	v_mfma_f32_16x16x32_bf16 v[152:155], v[238:241], v[56:59], v[152:155]
	ds_read_b128 v[230:233], v145 offset:19392
	s_waitcnt lgkmcnt(5)
	v_mfma_f32_16x16x32_bf16 v[202:205], v[184:187], v[40:43], v[202:205]
	v_mfma_f32_16x16x32_bf16 v[152:155], v[184:187], v[76:79], v[152:155]
	ds_read_b128 v[234:237], v145 offset:19456
	s_waitcnt lgkmcnt(5)
	v_mfma_f32_16x16x32_bf16 v[202:205], v[188:191], v[52:55], v[202:205]
	v_mfma_f32_16x16x32_bf16 v[152:155], v[188:191], v[68:71], v[152:155]
	ds_read_b128 v[238:241], v145 offset:19520
	s_waitcnt lgkmcnt(5)
	v_mfma_f32_16x16x32_bf16 v[210:213], v[192:195], v[36:39], 0
	v_mfma_f32_16x16x32_bf16 v[156:159], v[192:195], v[72:75], 0
	s_waitcnt lgkmcnt(4)
	v_mfma_f32_16x16x32_bf16 v[210:213], v[196:199], v[32:35], v[210:213]
	v_mfma_f32_16x16x32_bf16 v[156:159], v[196:199], v[64:67], v[156:159]
	s_waitcnt lgkmcnt(3)
	v_mfma_f32_16x16x32_bf16 v[210:213], v[206:209], v[28:31], v[210:213]
	v_mfma_f32_16x16x32_bf16 v[156:159], v[206:209], v[60:63], v[156:159]
	s_waitcnt lgkmcnt(2)
	v_mfma_f32_16x16x32_bf16 v[210:213], v[230:233], v[24:27], v[210:213]
	v_mfma_f32_16x16x32_bf16 v[156:159], v[230:233], v[56:59], v[156:159]
	s_waitcnt lgkmcnt(1)
	v_mfma_f32_16x16x32_bf16 v[210:213], v[234:237], v[40:43], v[210:213]
	v_mfma_f32_16x16x32_bf16 v[156:159], v[234:237], v[76:79], v[156:159]
	v_and_b32_e32 v146, 64, v217
	v_add_u32_e32 v146, 64, v146
	v_xor_b32_e32 v145, 16, v217
	v_cmp_lt_i32_e32 vcc, v145, v146
	s_waitcnt lgkmcnt(0)
; #define LAS __attribute__((address_space(3)))
; DEVINL unsigned cvt_pk_bf16(float lo, float hi) { const f32x2 v = {lo, hi}; return __builtin_bit_cast(unsigned, __builtin_convertvector(v, bf16x2_t)); }
; template <int DQK, int D1, int DV, bool MLA, int NQ>
; DEVINL void attn_block(LAS unsigned char* lds, const bf16_t* q, int ldq, const bf16_t* k1, int ld1, const bf16_t* k2, int ld2,
;                        const bf16_t* vt, int ldv, bf16_t* o, int ldo, int nt, int qtile0, const f32x2* cs, float sc) {
;     ...
;             for (int qi = 0; qi < NQ; ++qi) {
;                 float mx = s[qi][0][0];
; #pragma unroll
;                 for (int kb = 0; kb < 4; ++kb)
; #pragma unroll
;                     for (int i = 0; i < 4; ++i) mx = fmaxf(mx, s[qi][kb][i]);
;                 mx = fmaxf(mx, __shfl_xor(mx, 16)); mx = fmaxf(mx, __shfl_xor(mx, 32));
;                 const float mnew = fmaxf(mrun[qi], mx * sc), alpha = __builtin_amdgcn_exp2f(mrun[qi] - mnew);
;                 mrun[qi] = mnew; float ls = 0.f;
; #pragma unroll
;                 for (int kb = 0; kb < 4; ++kb)
; #pragma unroll
;                     for (int i = 0; i < 4; ++i) { const float p = __builtin_amdgcn_exp2f(s[qi][kb][i] * sc - mnew); s[qi][kb][i] = p; ls += p; }
;                 lrun[qi] = lrun[qi] * alpha + ls;
; #pragma unroll
;                 for (int i = 0; i < NDB; ++i) acc[qi][i] *= alpha;
; #pragma unroll
;                 for (int ks = 0; ks < 2; ++ks) { u32x4 pw; pw.x = cvt_pk_bf16(s[qi][2 * ks][0], s[qi][2 * ks][1]); pw.y = cvt_pk_bf16(s[qi][2 * ks][2], s[qi][2 * ks][3]); pw.z = cvt_pk_bf16(s[qi][2 * ks + 1][0], s[qi][2 * ks + 1][1]); pw.w = cvt_pk_bf16(s[qi][2 * ks + 1][2], s[qi][2 * ks + 1][3]);
;                     pf[qi][ks] = __builtin_bit_cast(bf16x8, pw); }
;             }
;     ...
;             for (int ks = 0; ks < 2; ++ks)
; #pragma unroll
;                 for (int db = 0; db < NDB; ++db) { const LAS unsigned char* vp = cb + 64 * KS + (db * 16 + fr) * VS + (32 * ks + 4 * fq) * 2;
;                     const u32x2 lo = *(const LAS u32x2*)vp, hi = *(const LAS u32x2*)(vp + 32);
;                     const bf16x8 a = __builtin_bit_cast(bf16x8, (u32x4){lo.x, lo.y, hi.x, hi.y});
	v_mfma_f32_16x16x32_bf16 v[210:213], v[238:241], v[52:55], v[210:213]
	v_cndmask_b32_e32 v145, v217, v145, vcc
	s_nop 1
	v_lshlrev_b32_e32 v184, 2, v145
	v_xor_b32_e32 v145, 32, v217
	v_cmp_lt_i32_e32 vcc, v145, v146
	v_max_f32_e32 v146, v136, v136
	v_mfma_f32_16x16x32_bf16 v[156:159], v[238:241], v[68:71], v[156:159]
	v_cndmask_b32_e32 v145, v217, v145, vcc
	v_lshlrev_b32_e32 v186, 2, v145
	v_max_f32_e32 v145, v137, v137
	v_max_f32_e32 v145, v146, v145
	v_max3_f32 v145, v145, v138, v139
	v_max3_f32 v145, v145, v140, v141
	v_max3_f32 v145, v145, v142, v143
	v_max3_f32 v145, v145, v202, v203
	v_max3_f32 v145, v145, v204, v205
	v_max3_f32 v145, v145, v210, v211
	v_max3_f32 v145, v145, v212, v213
	v_mov_b32_e32 v146, v145
	s_nop 1
	v_permlane16_swap_b32_e32 v145, v146
	v_max_f32_e32 v145, v145, v146
	v_mov_b32_e32 v146, v145
	s_nop 1
	v_permlane32_swap_b32_e32 v145, v146
	v_max_f32_e32 v145, v145, v146
	v_mul_f32_e32 v145, 0x3dd53b94, v145
	v_max_f32_e32 v146, v144, v144
	v_max_f32_e32 v227, v146, v145
	v_sub_f32_e32 v144, v144, v227
	v_fma_f32 v136, v136, s31, -v227
	v_exp_f32_e32 v183, v136
	v_fma_f32 v136, v137, s31, -v227
	v_exp_f32_e32 v214, v144
	v_exp_f32_e32 v185, v136
	v_fma_f32 v136, v138, s31, -v227
	v_exp_f32_e32 v187, v136
	v_fma_f32 v136, v139, s31, -v227
	v_exp_f32_e32 v189, v136
	v_fma_f32 v136, v140, s31, -v227
	v_exp_f32_e32 v191, v136
	v_fma_f32 v136, v141, s31, -v227
	v_pk_mul_f32 v[140:141], v[104:105], v[214:215] op_sel_hi:[1,0]
	v_pk_mul_f32 v[104:105], v[88:89], v[214:215] op_sel_hi:[1,0]
	v_pk_mul_f32 v[88:89], v[92:93], v[214:215] op_sel_hi:[1,0]
	v_max_f32_e32 v92, v133, v133
	v_max_f32_e32 v93, v132, v132
	v_max_f32_e32 v92, v93, v92
	v_max3_f32 v92, v92, v134, v135
	v_max3_f32 v92, v92, v148, v149
	v_max3_f32 v92, v92, v150, v151
	v_max3_f32 v92, v92, v152, v153
	v_max3_f32 v92, v92, v154, v155
	v_max3_f32 v92, v92, v156, v157
	v_max3_f32 v92, v92, v158, v159
	v_mov_b32_e32 v93, v92
	v_exp_f32_e32 v193, v136
	v_fma_f32 v136, v142, s31, -v227
	v_exp_f32_e32 v195, v136
	v_fma_f32 v136, v143, s31, -v227
	v_permlane16_swap_b32_e32 v92, v93
	v_max_f32_e32 v92, v92, v93
	v_mov_b32_e32 v93, v92
	v_pk_mul_f32 v[142:143], v[106:107], v[214:215] op_sel_hi:[1,0]
	v_pk_mul_f32 v[106:107], v[90:91], v[214:215] op_sel_hi:[1,0]
	v_pk_mul_f32 v[90:91], v[94:95], v[214:215] op_sel_hi:[1,0]
	v_exp_f32_e32 v197, v136
	v_permlane32_swap_b32_e32 v92, v93
	v_max_f32_e32 v92, v92, v93
	v_mul_f32_e32 v92, 0x3dd53b94, v92
	v_max_f32_e32 v93, v182, v182
	v_max_f32_e32 v228, v93, v92
	v_fma_f32 v92, v132, s31, -v228
	v_sub_f32_e32 v94, v182, v228
	v_exp_f32_e32 v182, v92
	v_fma_f32 v92, v133, s31, -v228
	v_exp_f32_e32 v184, v92
	v_fma_f32 v92, v134, s31, -v228
	v_exp_f32_e32 v186, v92
	v_fma_f32 v92, v135, s31, -v228
	v_exp_f32_e32 v188, v92
	v_fma_f32 v92, v148, s31, -v228
	v_exp_f32_e32 v190, v92
	v_fma_f32 v92, v149, s31, -v228
	v_exp_f32_e32 v192, v92
	v_fma_f32 v92, v150, s31, -v228
	v_exp_f32_e32 v194, v92
	v_fma_f32 v92, v151, s31, -v228
	v_exp_f32_e32 v196, v92
	v_fma_f32 v92, v152, s31, -v228
	v_exp_f32_e32 v198, v92
	v_pk_add_f32 v[92:93], v[182:183], 0 op_sel_hi:[1,0]
	v_fma_f32 v136, v202, s31, -v227
	v_pk_add_f32 v[92:93], v[184:185], v[92:93]
	v_exp_f32_e32 v199, v136
	v_pk_add_f32 v[92:93], v[186:187], v[92:93]
	v_fma_f32 v136, v203, s31, -v227
	v_pk_add_f32 v[92:93], v[188:189], v[92:93]
	v_fma_f32 v95, v153, s31, -v228
	v_pk_add_f32 v[92:93], v[190:191], v[92:93]
	v_exp_f32_e32 v201, v136
	v_fma_f32 v136, v204, s31, -v227
	v_pk_add_f32 v[92:93], v[192:193], v[92:93]
	v_exp_f32_e32 v200, v95
	v_fma_f32 v95, v154, s31, -v228
	v_exp_f32_e32 v203, v136
	v_fma_f32 v136, v205, s31, -v227
	v_pk_add_f32 v[92:93], v[194:195], v[92:93]
	v_exp_f32_e32 v202, v95
	v_fma_f32 v95, v155, s31, -v228
	v_exp_f32_e32 v205, v136
	v_fma_f32 v136, v210, s31, -v227
	v_pk_add_f32 v[92:93], v[196:197], v[92:93]
	v_exp_f32_e32 v204, v95
	v_fma_f32 v95, v156, s31, -v228
	v_exp_f32_e32 v207, v136
	v_fma_f32 v136, v211, s31, -v227
	v_pk_add_f32 v[92:93], v[198:199], v[92:93]
	v_exp_f32_e32 v206, v95
	v_fma_f32 v95, v157, s31, -v228
	v_exp_f32_e32 v209, v136
	v_fma_f32 v136, v212, s31, -v227
	v_exp_f32_e32 v208, v95
	v_fma_f32 v95, v158, s31, -v228
	v_pk_add_f32 v[92:93], v[200:201], v[92:93]
	v_exp_f32_e32 v211, v136
	v_fma_f32 v136, v213, s31, -v227
	v_exp_f32_e32 v210, v95
	v_fma_f32 v95, v159, s31, -v228
	v_pk_add_f32 v[92:93], v[202:203], v[92:93]
	v_exp_f32_e32 v213, v136
	v_exp_f32_e32 v212, v95
	v_pk_add_f32 v[92:93], v[204:205], v[92:93]
	v_exp_f32_e32 v156, v94
	v_pk_add_f32 v[92:93], v[206:207], v[92:93]
	v_mov_b32_e32 v157, v214
	v_pk_add_f32 v[92:93], v[208:209], v[92:93]
	v_pk_mul_f32 v[94:95], v[2:3], v[156:157] op_sel_hi:[1,0]
	v_pk_add_f32 v[92:93], v[210:211], v[92:93]
	v_pk_mul_f32 v[134:135], v[6:7], v[156:157] op_sel_hi:[1,0]
	v_pk_add_f32 v[92:93], v[212:213], v[92:93]
	v_pk_mul_f32 v[132:133], v[4:5], v[156:157] op_sel_hi:[1,0]
	v_pk_fma_f32 v[166:167], v[166:167], v[156:157], v[92:93]
	v_pk_mul_f32 v[92:93], v[0:1], v[156:157] op_sel_hi:[1,0]
	v_pk_mul_f32 v[154:155], v[10:11], v[156:157] op_sel_hi:[1,0]
	v_pk_mul_f32 v[152:153], v[8:9], v[156:157] op_sel_hi:[1,0]
	v_pk_mul_f32 v[150:151], v[18:19], v[156:157] op_sel_hi:[1,0]
	v_pk_mul_f32 v[148:149], v[16:17], v[156:157] op_sel_hi:[1,0]
	v_pk_mul_f32 v[18:19], v[14:15], v[156:157] op_sel_hi:[1,0]
	v_pk_mul_f32 v[16:17], v[12:13], v[156:157] op_sel_hi:[1,0]
	v_pk_mul_f32 v[14:15], v[22:23], v[156:157] op_sel_hi:[1,0]
	v_pk_mul_f32 v[12:13], v[20:21], v[156:157] op_sel_hi:[1,0]
	v_pk_mul_f32 v[10:11], v[46:47], v[156:157] op_sel_hi:[1,0]
	v_pk_mul_f32 v[8:9], v[44:45], v[156:157] op_sel_hi:[1,0]
	v_pk_mul_f32 v[2:3], v[50:51], v[156:157] op_sel_hi:[1,0]
	v_pk_mul_f32 v[0:1], v[48:49], v[156:157] op_sel_hi:[1,0]
	v_add3_u32 v156, s66, v160, v169
	v_mov_b32_e32 v229, v156
	ds_read_b64 v[230:231], v229 offset:25600
	ds_read_b64 v[232:233], v229 offset:25632
	ds_read_b64 v[234:235], v229 offset:27904
	ds_read_b64 v[236:237], v229 offset:27936
	ds_read_b64 v[238:239], v229 offset:30208
	ds_read_b64 v[240:241], v229 offset:30240
	ds_read_b64 v[242:243], v229 offset:32512
	ds_read_b64 v[244:245], v229 offset:32544
	ds_read_b64 v[246:247], v229 offset:34816
	ds_read_b64 v[248:249], v229 offset:34848
	v_cvt_pk_bf16_f32 v50, v206, v208
	v_add_u32_e32 v206, 0x6000, v156
	v_pk_mul_f32 v[146:147], v[102:103], v[214:215] op_sel_hi:[1,0]
	v_pk_mul_f32 v[144:145], v[100:101], v[214:215] op_sel_hi:[1,0]
	v_pk_mul_f32 v[138:139], v[98:99], v[214:215] op_sel_hi:[1,0]
	v_pk_mul_f32 v[102:103], v[86:87], v[214:215] op_sel_hi:[1,0]
	v_pk_mul_f32 v[100:101], v[84:85], v[214:215] op_sel_hi:[1,0]
	v_pk_mul_f32 v[98:99], v[82:83], v[214:215] op_sel_hi:[1,0]
	v_pk_mul_f32 v[82:83], v[130:131], v[214:215] op_sel_hi:[1,0]
	v_cvt_pk_bf16_f32 v84, v183, v185
	v_cvt_pk_bf16_f32 v85, v187, v189
	v_cvt_pk_bf16_f32 v86, v191, v193
	v_cvt_pk_bf16_f32 v87, v195, v197
	v_cvt_pk_bf16_f32 v130, v207, v209
	v_add_u32_e32 v207, 0x6800, v156
	s_waitcnt lgkmcnt(8)
; #define LAS __attribute__((address_space(3)))
; template <int DQK, int D1, int DV, bool MLA, int NQ>
; DEVINL void attn_block(LAS unsigned char* lds, const bf16_t* q, int ldq, const bf16_t* k1, int ld1, const bf16_t* k2, int ld2,
;                        const bf16_t* vt, int ldv, bf16_t* o, int ldo, int nt, int qtile0, const f32x2* cs, float sc) {
;     ...
;             for (int ks = 0; ks < 2; ++ks)
; #pragma unroll
;                 for (int db = 0; db < NDB; ++db) { const LAS unsigned char* vp = cb + 64 * KS + (db * 16 + fr) * VS + (32 * ks + 4 * fq) * 2;
;                     const u32x2 lo = *(const LAS u32x2*)vp, hi = *(const LAS u32x2*)(vp + 32);
;                     const bf16x8 a = __builtin_bit_cast(bf16x8, (u32x4){lo.x, lo.y, hi.x, hi.y});
; #pragma unroll
;                     for (int qi = 0; qi < NQ; ++qi) acc[qi][db] = __builtin_amdgcn_mfma_f32_16x16x32_bf16(a, pf[qi][ks], acc[qi][db], 0, 0, 0); }
	v_mfma_f32_16x16x32_bf16 v[44:47], v[230:233], v[84:87], v[144:147]
	v_cvt_pk_bf16_f32 v4, v182, v184
	v_cvt_pk_bf16_f32 v5, v186, v188
	v_cvt_pk_bf16_f32 v6, v190, v192
	v_cvt_pk_bf16_f32 v7, v194, v196
	v_add_u32_e32 v208, 0x7000, v156
	v_pk_mul_f32 v[136:137], v[96:97], v[214:215] op_sel_hi:[1,0]
	v_mfma_f32_16x16x32_bf16 v[20:23], v[230:233], v[4:7], v[92:95]
	ds_read_b64 v[230:231], v229 offset:37120
	ds_read_b64 v[232:233], v229 offset:37152
	v_add_u32_e32 v209, 0x7800, v156
	v_cvt_pk_bf16_f32 v51, v210, v212
	v_add_u32_e32 v210, 0x8800, v156
	s_waitcnt lgkmcnt(8)
	v_mfma_f32_16x16x32_bf16 v[92:95], v[234:237], v[84:87], v[140:143]
	v_cvt_pk_bf16_f32 v131, v211, v213
	v_add_u32_e32 v211, 0x9000, v156
	s_nop 0
	s_waitcnt lgkmcnt(6)
	v_mfma_f32_16x16x32_bf16 v[136:139], v[238:241], v[84:87], v[136:139]
	v_add_u32_e32 v212, 0x9800, v156
	v_add_u32_e32 v213, 0xa000, v156
	v_pk_mul_f32 v[96:97], v[80:81], v[214:215] op_sel_hi:[1,0]
	v_mfma_f32_16x16x32_bf16 v[140:143], v[238:241], v[4:7], v[152:155]
	ds_read_b64 v[238:239], v229 offset:39424
	ds_read_b64 v[240:241], v229 offset:39456
	v_mul_f32_e64 v80, v128, v214
	v_mul_f32_e64 v81, v129, v214
	v_cvt_pk_bf16_f32 v129, v203, v205
	v_cvt_pk_bf16_f32 v49, v202, v204
	v_mfma_f32_16x16x32_bf16 v[132:135], v[234:237], v[4:7], v[132:135]
	ds_read_b64 v[234:235], v229 offset:41728
	ds_read_b64 v[236:237], v229 offset:41760
	v_cvt_pk_bf16_f32 v128, v199, v201
	v_cvt_pk_bf16_f32 v48, v198, v200
	s_waitcnt lgkmcnt(8)
	v_mfma_f32_16x16x32_bf16 v[144:147], v[242:245], v[84:87], v[104:107]
	s_nop 2
	s_waitcnt lgkmcnt(6)
	v_mfma_f32_16x16x32_bf16 v[186:189], v[246:249], v[4:7], v[16:19]
	s_nop 2
	s_waitcnt lgkmcnt(4)
	v_mfma_f32_16x16x32_bf16 v[194:197], v[230:233], v[4:7], v[12:15]
	s_nop 2
	s_waitcnt lgkmcnt(2)
	v_mfma_f32_16x16x32_bf16 v[202:205], v[238:241], v[4:7], v[8:11]
	s_nop 2
	v_mfma_f32_16x16x32_bf16 v[148:151], v[242:245], v[4:7], v[148:151]
	ds_read_b64 v[242:243], v229 offset:25664
	ds_read_b64 v[244:245], v229 offset:25696
	v_mfma_f32_16x16x32_bf16 v[198:201], v[238:241], v[84:87], v[88:91]
	ds_read_b64 v[238:239], v229 offset:27968
	ds_read_b64 v[240:241], v229 offset:28000
	s_waitcnt lgkmcnt(4)
	v_mfma_f32_16x16x32_bf16 v[156:159], v[234:237], v[4:7], v[0:3]
	s_nop 1
	v_mfma_f32_16x16x32_bf16 v[182:185], v[246:249], v[84:87], v[100:103]
	ds_read_b64 v[246:247], v229 offset:32576
	ds_read_b64 v[248:249], v229 offset:32608
	v_mfma_f32_16x16x32_bf16 v[190:193], v[230:233], v[84:87], v[96:99]
	ds_read_b64 v[230:231], v229 offset:30272
	ds_read_b64 v[232:233], v229 offset:30304
	v_mfma_f32_16x16x32_bf16 v[152:155], v[234:237], v[84:87], v[80:83]
	ds_read_b64 v[234:235], v229 offset:34880
	ds_read_b64 v[236:237], v229 offset:34912
	s_waitcnt lgkmcnt(8)
	v_mfma_f32_16x16x32_bf16 v[100:103], v[242:245], v[128:131], v[44:47]
	v_mfma_f32_16x16x32_bf16 v[0:3], v[242:245], v[48:51], v[20:23]
	ds_read_b64 v[242:243], v229 offset:37184
	ds_read_b64 v[244:245], v229 offset:37216
	s_nop 1
	s_waitcnt lgkmcnt(8)
	v_mfma_f32_16x16x32_bf16 v[104:107], v[238:241], v[128:131], v[92:95]
	v_mfma_f32_16x16x32_bf16 v[4:7], v[238:241], v[48:51], v[132:135]
	ds_read_b64 v[238:239], v229 offset:39488
	ds_read_b64 v[240:241], v229 offset:39520
	s_waitcnt lgkmcnt(8)
	v_mfma_f32_16x16x32_bf16 v[88:91], v[246:249], v[128:131], v[144:147]
	s_nop 1
	v_mfma_f32_16x16x32_bf16 v[16:19], v[246:249], v[48:51], v[148:151]
	ds_read_b64 v[246:247], v229 offset:41792
	ds_read_b64 v[248:249], v229 offset:41824
	v_mov_b32_e32 v144, v227
	s_waitcnt lgkmcnt(8)
	v_mfma_f32_16x16x32_bf16 v[96:99], v[230:233], v[128:131], v[136:139]
	v_mfma_f32_16x16x32_bf16 v[8:11], v[230:233], v[48:51], v[140:143]
	s_waitcnt lgkmcnt(6)
	v_mfma_f32_16x16x32_bf16 v[84:87], v[234:237], v[128:131], v[182:185]
	v_mfma_f32_16x16x32_bf16 v[12:15], v[234:237], v[48:51], v[186:189]
	s_nop 1
	v_mov_b32_e32 v182, v228
	s_waitcnt lgkmcnt(4)
	v_mfma_f32_16x16x32_bf16 v[80:83], v[242:245], v[128:131], v[190:193]
	v_mfma_f32_16x16x32_bf16 v[20:23], v[242:245], v[48:51], v[194:197]
	s_waitcnt lgkmcnt(2)
	v_mfma_f32_16x16x32_bf16 v[92:95], v[238:241], v[128:131], v[198:201]
	v_mfma_f32_16x16x32_bf16 v[44:47], v[238:241], v[48:51], v[202:205]
	s_waitcnt lgkmcnt(0)
	v_mfma_f32_16x16x32_bf16 v[128:131], v[246:249], v[128:131], v[152:155]
	v_mfma_f32_16x16x32_bf16 v[48:51], v[246:249], v[48:51], v[156:159]
	s_branch .LBB0_910
; #define LAS __attribute__((address_space(3)))
; template <int DQK, int D1, int DV, bool MLA, int NQ>
; DEVINL void attn_block(LAS unsigned char* lds, const bf16_t* q, int ldq, const bf16_t* k1, int ld1, const bf16_t* k2, int ld2,
;                        const bf16_t* vt, int ldv, bf16_t* o, int ldo, int nt, int qtile0, const f32x2* cs, float sc) {
;     ...
;         if (j <= jmax) {
;             f32x4 s[NQ][4];
; #pragma unroll
;             for (int kb = 0; kb < 4; ++kb) {
; #pragma unroll
;                 for (int qi = 0; qi < NQ; ++qi) s[qi][kb] = (f32x4){0.f, 0.f, 0.f, 0.f};
; #pragma unroll
;                 for (int ks = 0; ks < NKS; ++ks) { const bf16x8 a = *(const LAS bf16x8*)(cb + (kb * 16 + fr) * KS + ks * 64 + fq * 16);
; #pragma unroll
;                     for (int qi = 0; qi < NQ; ++qi) s[qi][kb] = __builtin_amdgcn_mfma_f32_16x16x32_bf16(a, qf[qi][ks], s[qi][kb], 0, 0, 0); } }
.LBB0_913:
	v_cmp_gt_i32_e32 vcc, 3, v218
	s_and_saveexec_b64 s[2:3], vcc
	s_xor_b64 s[6:7], exec, s[2:3]
	v_mbcnt_hi_u32_b32 v108, -1, v216
	v_and_b32_e32 v24, 64, v108
	v_xor_b32_e32 v157, 16, v108
	v_add_u32_e32 v156, 64, v24
	v_xor_b32_e32 v158, 32, v108
	s_andn2_saveexec_b64 s[6:7], s[6:7]
	s_cbranch_execz .LBB0_908
	v_add3_u32 v140, s66, v168, v171
	ds_read_b128 v[108:111], v140
	ds_read_b128 v[116:119], v140 offset:64
	v_xor_b32_e32 v157, 16, v217
	v_xor_b32_e32 v158, 32, v217
	s_waitcnt lgkmcnt(1)
	v_mfma_f32_16x16x32_bf16 v[112:115], v[108:111], v[36:39], 0
	ds_read_b128 v[124:127], v140 offset:6464
	ds_read_b128 v[132:135], v140 offset:6720
	ds_read_b128 v[136:139], v140 offset:12864
	v_mfma_f32_16x16x32_bf16 v[108:111], v[108:111], v[72:75], 0
	s_waitcnt lgkmcnt(3)
	v_mfma_f32_16x16x32_bf16 v[112:115], v[116:119], v[32:35], v[112:115]
	v_mfma_f32_16x16x32_bf16 v[108:111], v[116:119], v[64:67], v[108:111]
	ds_read_b128 v[116:119], v140 offset:128
	s_waitcnt lgkmcnt(0)
	v_mfma_f32_16x16x32_bf16 v[112:115], v[116:119], v[28:31], v[112:115]
	v_mfma_f32_16x16x32_bf16 v[108:111], v[116:119], v[60:63], v[108:111]
	ds_read_b128 v[116:119], v140 offset:192
	s_waitcnt lgkmcnt(0)
	v_mfma_f32_16x16x32_bf16 v[112:115], v[116:119], v[24:27], v[112:115]
	v_mfma_f32_16x16x32_bf16 v[108:111], v[116:119], v[56:59], v[108:111]
	ds_read_b128 v[116:119], v140 offset:256
	s_waitcnt lgkmcnt(0)
	v_mfma_f32_16x16x32_bf16 v[112:115], v[116:119], v[40:43], v[112:115]
	v_mfma_f32_16x16x32_bf16 v[108:111], v[116:119], v[76:79], v[108:111]
	ds_read_b128 v[116:119], v140 offset:320
	s_waitcnt lgkmcnt(0)
	v_mfma_f32_16x16x32_bf16 v[120:123], v[116:119], v[52:55], v[112:115]
	s_nop 3
	ds_read_b128 v[112:115], v140 offset:6400
	v_mfma_f32_16x16x32_bf16 v[108:111], v[116:119], v[68:71], v[108:111]
	s_waitcnt lgkmcnt(0)
	v_mfma_f32_16x16x32_bf16 v[116:119], v[112:115], v[36:39], 0
	v_mfma_f32_16x16x32_bf16 v[112:115], v[112:115], v[72:75], 0
	v_mfma_f32_16x16x32_bf16 v[116:119], v[124:127], v[32:35], v[116:119]
	v_mfma_f32_16x16x32_bf16 v[112:115], v[124:127], v[64:67], v[112:115]
	ds_read_b128 v[124:127], v140 offset:6528
	s_waitcnt lgkmcnt(0)
	v_mfma_f32_16x16x32_bf16 v[116:119], v[124:127], v[28:31], v[116:119]
	v_mfma_f32_16x16x32_bf16 v[112:115], v[124:127], v[60:63], v[112:115]
	ds_read_b128 v[124:127], v140 offset:6592
	s_waitcnt lgkmcnt(0)
	v_mfma_f32_16x16x32_bf16 v[116:119], v[124:127], v[24:27], v[116:119]
	v_mfma_f32_16x16x32_bf16 v[112:115], v[124:127], v[56:59], v[112:115]
	ds_read_b128 v[124:127], v140 offset:6656
	s_waitcnt lgkmcnt(0)
	v_mfma_f32_16x16x32_bf16 v[116:119], v[124:127], v[40:43], v[116:119]
	v_mfma_f32_16x16x32_bf16 v[112:115], v[124:127], v[76:79], v[112:115]
	v_mfma_f32_16x16x32_bf16 v[124:127], v[132:135], v[52:55], v[116:119]
	s_nop 5
	ds_read_b128 v[116:119], v140 offset:12800
	v_mfma_f32_16x16x32_bf16 v[112:115], v[132:135], v[68:71], v[112:115]
	s_waitcnt lgkmcnt(0)
	v_mfma_f32_16x16x32_bf16 v[132:135], v[116:119], v[36:39], 0
	v_mfma_f32_16x16x32_bf16 v[116:119], v[116:119], v[72:75], 0
	v_mfma_f32_16x16x32_bf16 v[132:135], v[136:139], v[32:35], v[132:135]
	v_mfma_f32_16x16x32_bf16 v[116:119], v[136:139], v[64:67], v[116:119]
	ds_read_b128 v[136:139], v140 offset:12928
	s_waitcnt lgkmcnt(0)
	v_mfma_f32_16x16x32_bf16 v[132:135], v[136:139], v[28:31], v[132:135]
	v_mfma_f32_16x16x32_bf16 v[116:119], v[136:139], v[60:63], v[116:119]
	ds_read_b128 v[136:139], v140 offset:12992
	s_waitcnt lgkmcnt(0)
	v_mfma_f32_16x16x32_bf16 v[132:135], v[136:139], v[24:27], v[132:135]
	v_mfma_f32_16x16x32_bf16 v[116:119], v[136:139], v[56:59], v[116:119]
	ds_read_b128 v[136:139], v140 offset:13056
	s_waitcnt lgkmcnt(0)
	v_mfma_f32_16x16x32_bf16 v[132:135], v[136:139], v[40:43], v[132:135]
	v_mfma_f32_16x16x32_bf16 v[116:119], v[136:139], v[76:79], v[116:119]
	ds_read_b128 v[136:139], v140 offset:13120
	s_waitcnt lgkmcnt(0)
	v_mfma_f32_16x16x32_bf16 v[146:149], v[136:139], v[52:55], v[132:135]
	s_nop 3
	ds_read_b128 v[132:135], v140 offset:19200
	s_waitcnt lgkmcnt(0)
	v_mfma_f32_16x16x32_bf16 v[36:39], v[132:135], v[36:39], 0
	v_mfma_f32_16x16x32_bf16 v[72:75], v[132:135], v[72:75], 0
	ds_read_b128 v[132:135], v140 offset:19264
	s_waitcnt lgkmcnt(0)
	v_mfma_f32_16x16x32_bf16 v[32:35], v[132:135], v[32:35], v[36:39]
	v_mfma_f32_16x16x32_bf16 v[36:39], v[132:135], v[64:67], v[72:75]
	ds_read_b128 v[64:67], v140 offset:19328
	s_waitcnt lgkmcnt(0)
	v_mfma_f32_16x16x32_bf16 v[28:31], v[64:67], v[28:31], v[32:35]
	v_mfma_f32_16x16x32_bf16 v[32:35], v[64:67], v[60:63], v[36:39]
	s_nop 3
	ds_read_b128 v[36:39], v140 offset:19392
	s_waitcnt lgkmcnt(0)
	v_mfma_f32_16x16x32_bf16 v[24:27], v[36:39], v[24:27], v[28:31]
	v_mfma_f32_16x16x32_bf16 v[28:31], v[36:39], v[56:59], v[32:35]
	s_nop 2
	ds_read_b128 v[32:35], v140 offset:19456
	s_waitcnt lgkmcnt(0)
	v_mfma_f32_16x16x32_bf16 v[24:27], v[32:35], v[40:43], v[24:27]
	v_mfma_f32_16x16x32_bf16 v[28:31], v[32:35], v[76:79], v[28:31]
	ds_read_b128 v[32:35], v140 offset:19520
	v_max_f32_e32 v79, v109, v109
	s_waitcnt lgkmcnt(0)
; DEVINL unsigned cvt_pk_bf16(float lo, float hi) { const f32x2 v = {lo, hi}; return __builtin_bit_cast(unsigned, __builtin_convertvector(v, bf16x2_t)); }
; template <int DQK, int D1, int DV, bool MLA, int NQ>
; DEVINL void attn_block(LAS unsigned char* lds, const bf16_t* q, int ldq, const bf16_t* k1, int ld1, const bf16_t* k2, int ld2,
;                        const bf16_t* vt, int ldv, bf16_t* o, int ldo, int nt, int qtile0, const f32x2* cs, float sc) {
;     ...
;             for (int qi = 0; qi < NQ; ++qi) {
;                 float mx = s[qi][0][0];
; #pragma unroll
;                 for (int kb = 0; kb < 4; ++kb)
; #pragma unroll
;                     for (int i = 0; i < 4; ++i) mx = fmaxf(mx, s[qi][kb][i]);
;                 mx = fmaxf(mx, __shfl_xor(mx, 16)); mx = fmaxf(mx, __shfl_xor(mx, 32));
;                 const float mnew = fmaxf(mrun[qi], mx * sc), alpha = __builtin_amdgcn_exp2f(mrun[qi] - mnew);
;                 mrun[qi] = mnew; float ls = 0.f;
; #pragma unroll
;                 for (int kb = 0; kb < 4; ++kb)
; #pragma unroll
;                     for (int i = 0; i < 4; ++i) { const float p = __builtin_amdgcn_exp2f(s[qi][kb][i] * sc - mnew); s[qi][kb][i] = p; ls += p; }
;                 lrun[qi] = lrun[qi] * alpha + ls;
; #pragma unroll
;                 for (int i = 0; i < NDB; ++i) acc[qi][i] *= alpha;
; #pragma unroll
;                 for (int ks = 0; ks < 2; ++ks) { u32x4 pw; pw.x = cvt_pk_bf16(s[qi][2 * ks][0], s[qi][2 * ks][1]); pw.y = cvt_pk_bf16(s[qi][2 * ks][2], s[qi][2 * ks][3]); pw.z = cvt_pk_bf16(s[qi][2 * ks + 1][0], s[qi][2 * ks + 1][1]); pw.w = cvt_pk_bf16(s[qi][2 * ks + 1][2], s[qi][2 * ks + 1][3]);
;                     pf[qi][ks] = __builtin_bit_cast(bf16x8, pw); }
;             }
	v_mfma_f32_16x16x32_bf16 v[40:43], v[32:35], v[68:71], v[28:31]
	s_nop 3
	v_and_b32_e32 v28, 64, v217
	v_add_u32_e32 v156, 64, v28
	v_cmp_lt_i32_e32 vcc, v157, v156
	v_max_f32_e32 v29, v120, v120
	v_mfma_f32_16x16x32_bf16 v[24:27], v[32:35], v[52:55], v[24:27]
	v_cndmask_b32_e32 v28, v217, v157, vcc
	v_cmp_lt_i32_e32 vcc, v158, v156
	v_lshlrev_b32_e32 v77, 2, v28
	v_mfma_f32_16x16x32_bf16 v[116:119], v[136:139], v[68:71], v[116:119]
	v_cndmask_b32_e32 v28, v217, v158, vcc
	v_lshlrev_b32_e32 v78, 2, v28
	v_max_f32_e32 v28, v121, v121
	v_max_f32_e32 v28, v29, v28
	v_max3_f32 v28, v28, v122, v123
	v_max3_f32 v28, v28, v124, v125
	v_max3_f32 v28, v28, v126, v127
	v_max3_f32 v28, v28, v146, v147
	v_max3_f32 v28, v28, v148, v149
	v_max3_f32 v28, v28, v24, v25
	v_max3_f32 v28, v28, v26, v27
	v_mov_b32_e32 v29, v28
	s_nop 1
	v_permlane16_swap_b32_e32 v28, v29
	v_max_f32_e32 v28, v28, v29
	v_mov_b32_e32 v29, v28
	s_nop 1
	v_permlane32_swap_b32_e32 v28, v29
	v_max_f32_e32 v28, v28, v29
	v_mul_f32_e32 v28, 0x3dd53b94, v28
	v_max_f32_e32 v29, v144, v144
	v_max_f32_e32 v28, v29, v28
	v_sub_f32_e32 v29, v144, v28
	v_fma_f32 v30, v120, s31, -v28
	v_exp_f32_e32 v76, v29
	v_exp_f32_e32 v133, v30
	v_fma_f32 v30, v121, s31, -v28
	v_exp_f32_e32 v121, v30
	v_fma_f32 v30, v122, s31, -v28
	v_exp_f32_e32 v135, v30
	v_fma_f32 v30, v123, s31, -v28
	v_exp_f32_e32 v123, v30
	v_fma_f32 v30, v124, s31, -v28
	v_pk_mul_f32 v[52:53], v[80:81], v[76:77] op_sel_hi:[1,0]
	v_max_f32_e32 v80, v108, v108
	v_exp_f32_e32 v137, v30
	v_fma_f32 v30, v125, s31, -v28
	v_max_f32_e32 v79, v80, v79
	v_exp_f32_e32 v125, v30
	v_fma_f32 v30, v126, s31, -v28
	v_max3_f32 v79, v79, v110, v111
	v_exp_f32_e32 v139, v30
	v_fma_f32 v30, v127, s31, -v28
	v_max3_f32 v79, v79, v112, v113
	v_exp_f32_e32 v127, v30
	v_fma_f32 v30, v146, s31, -v28
	v_max3_f32 v79, v79, v114, v115
	v_exp_f32_e32 v141, v30
	v_fma_f32 v30, v147, s31, -v28
	v_max3_f32 v79, v79, v116, v117
	v_exp_f32_e32 v143, v30
	v_fma_f32 v30, v148, s31, -v28
	v_fma_f32 v24, v24, s31, -v28
	v_max3_f32 v79, v79, v118, v119
	v_exp_f32_e32 v145, v30
	v_fma_f32 v30, v149, s31, -v28
	v_exp_f32_e32 v149, v24
	v_fma_f32 v24, v25, s31, -v28
	v_max3_f32 v79, v79, v40, v41
	v_exp_f32_e32 v151, v24
	v_fma_f32 v24, v26, s31, -v28
	v_max3_f32 v79, v79, v42, v43
	v_exp_f32_e32 v147, v30
	v_exp_f32_e32 v153, v24
	v_fma_f32 v24, v27, s31, -v28
	v_pk_mul_f32 v[74:75], v[102:103], v[76:77] op_sel_hi:[1,0]
	v_pk_mul_f32 v[72:73], v[100:101], v[76:77] op_sel_hi:[1,0]
	v_pk_mul_f32 v[70:71], v[106:107], v[76:77] op_sel_hi:[1,0]
	v_pk_mul_f32 v[68:69], v[104:105], v[76:77] op_sel_hi:[1,0]
	v_pk_mul_f32 v[66:67], v[98:99], v[76:77] op_sel_hi:[1,0]
	v_pk_mul_f32 v[64:65], v[96:97], v[76:77] op_sel_hi:[1,0]
	v_pk_mul_f32 v[62:63], v[90:91], v[76:77] op_sel_hi:[1,0]
	v_pk_mul_f32 v[60:61], v[88:89], v[76:77] op_sel_hi:[1,0]
	v_pk_mul_f32 v[58:59], v[86:87], v[76:77] op_sel_hi:[1,0]
	v_pk_mul_f32 v[56:57], v[84:85], v[76:77] op_sel_hi:[1,0]
	v_pk_mul_f32 v[54:55], v[82:83], v[76:77] op_sel_hi:[1,0]
	v_pk_mul_f32 v[38:39], v[94:95], v[76:77] op_sel_hi:[1,0]
	v_pk_mul_f32 v[36:37], v[92:93], v[76:77] op_sel_hi:[1,0]
	v_pk_mul_f32 v[30:31], v[130:131], v[76:77] op_sel_hi:[1,0]
	v_pk_mul_f32 v[28:29], v[128:129], v[76:77] op_sel_hi:[1,0]
	v_mov_b32_e32 v77, v79
	v_mov_b32_e32 v78, v79
	v_add3_u32 v96, s66, v160, v169
	v_add_u32_e32 v97, 0x6000, v96
	v_cvt_pk_bf16_f32 v32, v133, v121
	v_cvt_pk_bf16_f32 v33, v135, v123
	v_permlane16_swap_b32_e32 v77, v78
	v_max_f32_e32 v77, v77, v78
	v_mov_b32_e32 v78, v77
	v_cvt_pk_bf16_f32 v34, v137, v125
	v_cvt_pk_bf16_f32 v35, v139, v127
	v_exp_f32_e32 v155, v24
	v_cvt_pk_bf16_f32 v24, v141, v143
	v_permlane32_swap_b32_e32 v77, v78
	v_max_f32_e32 v77, v77, v78
	v_mul_f32_e32 v77, 0x3dd53b94, v77
	v_max_f32_e32 v78, v182, v182
	v_max_f32_e32 v77, v78, v77
	v_fma_f32 v78, v108, s31, -v77
	v_exp_f32_e32 v132, v78
	v_fma_f32 v78, v109, s31, -v77
	v_exp_f32_e32 v120, v78
	v_fma_f32 v78, v110, s31, -v77
	v_exp_f32_e32 v134, v78
	v_fma_f32 v78, v111, s31, -v77
	v_exp_f32_e32 v122, v78
	v_fma_f32 v78, v112, s31, -v77
	v_fma_f32 v40, v40, s31, -v77
	v_exp_f32_e32 v136, v78
	v_fma_f32 v78, v113, s31, -v77
	v_exp_f32_e32 v148, v40
	v_fma_f32 v40, v41, s31, -v77
	v_exp_f32_e32 v124, v78
	v_pk_add_f32 v[78:79], v[132:133], 0 op_sel_hi:[1,0]
	v_exp_f32_e32 v150, v40
	v_fma_f32 v40, v42, s31, -v77
	v_sub_f32_e32 v80, v182, v77
	v_pk_add_f32 v[78:79], v[120:121], v[78:79]
	v_fma_f32 v81, v114, s31, -v77
	v_exp_f32_e32 v152, v40
	v_fma_f32 v40, v43, s31, -v77
	v_pk_add_f32 v[78:79], v[134:135], v[78:79]
	v_exp_f32_e32 v138, v81
	v_fma_f32 v81, v115, s31, -v77
	v_exp_f32_e32 v154, v40
	v_exp_f32_e32 v40, v80
	v_pk_add_f32 v[78:79], v[122:123], v[78:79]
	v_exp_f32_e32 v126, v81
	v_fma_f32 v81, v116, s31, -v77
	v_pk_add_f32 v[78:79], v[136:137], v[78:79]
	v_exp_f32_e32 v140, v81
	v_fma_f32 v81, v117, s31, -v77
	v_pk_add_f32 v[78:79], v[124:125], v[78:79]
	v_exp_f32_e32 v142, v81
	v_fma_f32 v81, v118, s31, -v77
	v_mov_b32_e32 v41, v76
	v_exp_f32_e32 v144, v81
	v_fma_f32 v81, v119, s31, -v77
	v_pk_add_f32 v[42:43], v[138:139], v[78:79]
	v_pk_mul_f32 v[78:79], v[18:19], v[40:41] op_sel_hi:[1,0]
	v_pk_mul_f32 v[76:77], v[16:17], v[40:41] op_sel_hi:[1,0]
	v_pk_mul_f32 v[18:19], v[14:15], v[40:41] op_sel_hi:[1,0]
	v_pk_mul_f32 v[16:17], v[12:13], v[40:41] op_sel_hi:[1,0]
	v_pk_mul_f32 v[14:15], v[22:23], v[40:41] op_sel_hi:[1,0]
	v_pk_mul_f32 v[12:13], v[20:21], v[40:41] op_sel_hi:[1,0]
	ds_read2_b64 v[20:23], v97 offset0:128 offset1:132
	v_pk_mul_f32 v[90:91], v[2:3], v[40:41] op_sel_hi:[1,0]
	v_pk_mul_f32 v[88:89], v[0:1], v[40:41] op_sel_hi:[1,0]
	v_pk_mul_f32 v[86:87], v[6:7], v[40:41] op_sel_hi:[1,0]
	v_pk_mul_f32 v[84:85], v[4:5], v[40:41] op_sel_hi:[1,0]
	v_cvt_pk_bf16_f32 v4, v132, v120
	v_cvt_pk_bf16_f32 v5, v134, v122
	v_cvt_pk_bf16_f32 v6, v136, v124
	v_cvt_pk_bf16_f32 v7, v138, v126
	v_exp_f32_e32 v146, v81
	v_pk_mul_f32 v[82:83], v[10:11], v[40:41] op_sel_hi:[1,0]
	v_pk_mul_f32 v[80:81], v[8:9], v[40:41] op_sel_hi:[1,0]
	v_pk_mul_f32 v[10:11], v[46:47], v[40:41] op_sel_hi:[1,0]
	v_pk_mul_f32 v[8:9], v[44:45], v[40:41] op_sel_hi:[1,0]
	s_waitcnt lgkmcnt(0)
; #define LAS __attribute__((address_space(3)))
; DEVINL unsigned cvt_pk_bf16(float lo, float hi) { const f32x2 v = {lo, hi}; return __builtin_bit_cast(unsigned, __builtin_convertvector(v, bf16x2_t)); }
; template <int DQK, int D1, int DV, bool MLA, int NQ>
; DEVINL void attn_block(LAS unsigned char* lds, const bf16_t* q, int ldq, const bf16_t* k1, int ld1, const bf16_t* k2, int ld2,
;                        const bf16_t* vt, int ldv, bf16_t* o, int ldo, int nt, int qtile0, const f32x2* cs, float sc) {
;     ...
;                 lrun[qi] = lrun[qi] * alpha + ls;
; #pragma unroll
;                 for (int i = 0; i < NDB; ++i) acc[qi][i] *= alpha;
; #pragma unroll
;                 for (int ks = 0; ks < 2; ++ks) { u32x4 pw; pw.x = cvt_pk_bf16(s[qi][2 * ks][0], s[qi][2 * ks][1]); pw.y = cvt_pk_bf16(s[qi][2 * ks][2], s[qi][2 * ks][3]); pw.z = cvt_pk_bf16(s[qi][2 * ks + 1][0], s[qi][2 * ks + 1][1]); pw.w = cvt_pk_bf16(s[qi][2 * ks + 1][2], s[qi][2 * ks + 1][3]);
;                     pf[qi][ks] = __builtin_bit_cast(bf16x8, pw); }
;             }
; #pragma unroll
;             for (int ks = 0; ks < 2; ++ks)
; #pragma unroll
;                 for (int db = 0; db < NDB; ++db) { const LAS unsigned char* vp = cb + 64 * KS + (db * 16 + fr) * VS + (32 * ks + 4 * fq) * 2;
;                     const u32x2 lo = *(const LAS u32x2*)vp, hi = *(const LAS u32x2*)(vp + 32);
;                     const bf16x8 a = __builtin_bit_cast(bf16x8, (u32x4){lo.x, lo.y, hi.x, hi.y});
; #pragma unroll
;                     for (int qi = 0; qi < NQ; ++qi) acc[qi][db] = __builtin_amdgcn_mfma_f32_16x16x32_bf16(a, pf[qi][ks], acc[qi][db], 0, 0, 0); }
	v_mfma_f32_16x16x32_bf16 v[44:47], v[20:23], v[32:35], v[72:75]
	v_mul_f32_e64 v2, v50, v40
	v_mul_f32_e64 v3, v51, v40
	v_pk_mul_f32 v[0:1], v[48:49], v[40:41] op_sel_hi:[1,0]
	v_add_u32_e32 v112, 0x9000, v96
	v_mfma_f32_16x16x32_bf16 v[20:23], v[20:23], v[4:7], v[88:91]
	v_add_u32_e32 v113, 0x9800, v96
	v_add_u32_e32 v114, 0xa000, v96
	v_pk_add_f32 v[42:43], v[126:127], v[42:43]
	v_add_u32_e32 v88, 0x6800, v96
	ds_read2_b64 v[72:75], v88 offset0:160 offset1:164
	s_waitcnt lgkmcnt(0)
	v_mfma_f32_16x16x32_bf16 v[48:51], v[72:75], v[32:35], v[68:71]
	v_add_f32_e64 v42, v140, v42
	v_add_f32_e64 v43, v141, v43
	v_cvt_pk_bf16_f32 v25, v145, v147
	v_pk_add_f32 v[42:43], v[142:143], v[42:43]
	v_mfma_f32_16x16x32_bf16 v[68:71], v[72:75], v[4:7], v[84:87]
	v_add_f32_e64 v42, v144, v42
	v_add_f32_e64 v43, v145, v43
	v_cvt_pk_bf16_f32 v26, v149, v151
	v_pk_add_f32 v[42:43], v[146:147], v[42:43]
	v_add_u32_e32 v84, 0x7000, v96
	ds_read2_b64 v[72:75], v84 offset0:192 offset1:196
	v_add_u32_e32 v85, 0x7800, v96
	s_waitcnt lgkmcnt(0)
	v_mfma_f32_16x16x32_bf16 v[64:67], v[72:75], v[32:35], v[64:67]
	v_add_u32_e32 v86, 0x8800, v96
	v_pk_add_f32 v[42:43], v[148:149], v[42:43]
	v_cvt_pk_bf16_f32 v27, v153, v155
	v_mfma_f32_16x16x32_bf16 v[72:75], v[72:75], v[4:7], v[80:83]
	v_add_f32_e64 v42, v150, v42
	v_add_f32_e64 v43, v151, v43
	v_pk_add_f32 v[42:43], v[152:153], v[42:43]
	ds_read2_b64 v[80:83], v85 offset0:224 offset1:228
	s_waitcnt lgkmcnt(0)
	v_mfma_f32_16x16x32_bf16 v[60:63], v[80:83], v[32:35], v[60:63]
	v_add_f32_e64 v42, v154, v42
	v_add_f32_e64 v43, v155, v43
	v_pk_fma_f32 v[166:167], v[166:167], v[40:41], v[42:43]
	v_mfma_f32_16x16x32_bf16 v[76:79], v[80:83], v[4:7], v[76:79]
	ds_read2_b64 v[80:83], v86 offset1:4
	v_cvt_pk_bf16_f32 v40, v140, v142
	v_cvt_pk_bf16_f32 v41, v144, v146
	s_waitcnt lgkmcnt(0)
	v_mfma_f32_16x16x32_bf16 v[56:59], v[80:83], v[32:35], v[56:59]
	v_cvt_pk_bf16_f32 v42, v148, v150
	v_cvt_pk_bf16_f32 v43, v152, v154
	v_mfma_f32_16x16x32_bf16 v[80:83], v[80:83], v[4:7], v[16:19]
	s_nop 2
	ds_read2_b64 v[16:19], v112 offset0:32 offset1:36
	s_waitcnt lgkmcnt(0)
	v_mfma_f32_16x16x32_bf16 v[92:95], v[16:19], v[4:7], v[12:15]
	s_nop 2
	ds_read2_b64 v[12:15], v113 offset0:64 offset1:68
	s_waitcnt lgkmcnt(0)
	v_mfma_f32_16x16x32_bf16 v[108:111], v[12:15], v[4:7], v[8:11]
	s_nop 2
	ds_read2_b64 v[8:11], v114 offset0:96 offset1:100
	v_mfma_f32_16x16x32_bf16 v[52:55], v[16:19], v[32:35], v[52:55]
	v_mfma_f32_16x16x32_bf16 v[36:39], v[12:15], v[32:35], v[36:39]
	ds_read2_b64 v[12:15], v85 offset0:232 offset1:236
	s_waitcnt lgkmcnt(1)
	v_mfma_f32_16x16x32_bf16 v[28:31], v[8:11], v[32:35], v[28:31]
	v_mfma_f32_16x16x32_bf16 v[32:35], v[8:11], v[4:7], v[0:3]
	ds_read2_b64 v[4:7], v88 offset0:168 offset1:172
	ds_read2_b64 v[8:11], v84 offset0:200 offset1:204
	s_nop 0
	ds_read2_b64 v[0:3], v97 offset0:136 offset1:140
	s_waitcnt lgkmcnt(0)
	v_mfma_f32_16x16x32_bf16 v[100:103], v[0:3], v[24:27], v[44:47]
	s_nop 2
	ds_read2_b64 v[44:47], v113 offset0:72 offset1:76
	v_mfma_f32_16x16x32_bf16 v[0:3], v[0:3], v[40:43], v[20:23]
	v_mfma_f32_16x16x32_bf16 v[88:91], v[12:15], v[24:27], v[60:63]
	s_nop 1
	ds_read2_b64 v[20:23], v112 offset0:40 offset1:44
	v_mfma_f32_16x16x32_bf16 v[16:19], v[12:15], v[40:43], v[76:79]
	ds_read2_b64 v[12:15], v86 offset0:8 offset1:12
	s_waitcnt lgkmcnt(0)
	v_mfma_f32_16x16x32_bf16 v[84:87], v[12:15], v[24:27], v[56:59]
	v_mfma_f32_16x16x32_bf16 v[12:15], v[12:15], v[40:43], v[80:83]
	v_mfma_f32_16x16x32_bf16 v[80:83], v[20:23], v[24:27], v[52:55]
	v_mfma_f32_16x16x32_bf16 v[20:23], v[20:23], v[40:43], v[92:95]
	v_mfma_f32_16x16x32_bf16 v[92:95], v[44:47], v[24:27], v[36:39]
	s_nop 2
	ds_read2_b64 v[36:39], v114 offset0:104 offset1:108
	v_mfma_f32_16x16x32_bf16 v[104:107], v[4:7], v[24:27], v[48:51]
	v_mfma_f32_16x16x32_bf16 v[4:7], v[4:7], v[40:43], v[68:71]
	v_mfma_f32_16x16x32_bf16 v[96:99], v[8:11], v[24:27], v[64:67]
	v_mfma_f32_16x16x32_bf16 v[8:11], v[8:11], v[40:43], v[72:75]
	v_mfma_f32_16x16x32_bf16 v[44:47], v[44:47], v[40:43], v[108:111]
	s_waitcnt lgkmcnt(0)
	v_mfma_f32_16x16x32_bf16 v[128:131], v[36:39], v[24:27], v[28:31]
	s_nop 0
	v_mov_b32_e32 v108, v217
	v_mfma_f32_16x16x32_bf16 v[48:51], v[36:39], v[40:43], v[32:35]
	s_branch .LBB0_908

; #define LAS __attribute__((address_space(3)))
; template <int DQK, int D1, int DV, bool MLA, int NQ>
; DEVINL void attn_block(LAS unsigned char* lds, const bf16_t* q, int ldq, const bf16_t* k1, int ld1, const bf16_t* k2, int ld2,
;                        const bf16_t* vt, int ldv, bf16_t* o, int ldo, int nt, int qtile0, const f32x2* cs, float sc) {
;     ...
;         for (int i = 0; i < NC1; ++i) { const int c = tid + i * 512, row = c / CPR1, cc = c % CPR1; r1[i] = *(const u32x4*)(k1 + (size_t)(key0 + row) * ld1 + cc * 8); }
;         if (D2 > 0) { const int row = tid >> 3, cc = tid & 7; r2 = *(const u32x4*)(k2 + (size_t)(key0 + row) * ld2 + cc * 8); }
; #pragma unroll
;         for (int i = 0; i < NCV; ++i) { const int c = tid + i * 512, row = c >> 3, cc = c & 7; rv[i] = *(const u32x4*)(vt + (size_t)row * ldv + key0 + cc * 8); }
;     ...
;     for (int j = 0; j < nt; ++j) {
;         LAS unsigned char* cb = lds + (j & 1) * BUF;
;         if (j + 1 < nt) gload((j + 1) * 64);
;         if (j <= jmax) {
;             f32x4 s[NQ][4];
; #pragma unroll
;             for (int kb = 0; kb < 4; ++kb) {
; #pragma unroll
;                 for (int qi = 0; qi < NQ; ++qi) s[qi][kb] = (f32x4){0.f, 0.f, 0.f, 0.f};
; #pragma unroll
;                 for (int ks = 0; ks < NKS; ++ks) { const bf16x8 a = *(const LAS bf16x8*)(cb + (kb * 16 + fr) * KS + ks * 64 + fq * 16);
; #pragma unroll
;                     for (int qi = 0; qi < NQ; ++qi) s[qi][kb] = __builtin_amdgcn_mfma_f32_16x16x32_bf16(a, qf[qi][ks], s[qi][kb], 0, 0, 0); } }
.LBB0_1552:
	s_bitcmp1_b32 s16, 0
	s_cselect_b32 s24, 0, 0x11400
	s_cselect_b32 s17, 0x11400, 0
	s_add_i32 s24, s24, 16
	v_mov_b32_e32 v193, v156
	v_add3_u32 v156, s24, v128, v170
	ds_read_b128 v[172:175], v156
	ds_read_b128 v[176:179], v156 offset:64
	v_mov_b32_e32 v192, v171
	v_lshl_add_u64 v[96:97], s[20:21], 0, v[150:151]
	global_load_dwordx4 v[96:99], v[96:97], off
	v_lshl_add_u64 v[100:101], s[20:21], 0, v[148:149]
	global_load_dwordx4 v[100:103], v[100:101], off
	s_waitcnt vmcnt(9) lgkmcnt(1)
	v_mfma_f32_16x16x32_bf16 v[172:175], v[172:175], v[60:63], 0
	v_lshl_add_u64 v[104:105], s[20:21], 0, v[146:147]
	ds_read_b128 v[180:183], v156 offset:8512
	global_load_dwordx4 v[104:107], v[104:105], off
	s_waitcnt vmcnt(9) lgkmcnt(1)
	v_mfma_f32_16x16x32_bf16 v[172:175], v[176:179], v[56:59], v[172:175]
	ds_read_b128 v[176:179], v156 offset:128
	v_lshl_add_u64 v[108:109], s[20:21], 0, v[144:145]
	global_load_dwordx4 v[108:111], v[108:109], off
	v_lshl_add_u64 v[112:113], s[20:21], 0, v[136:137]
	global_load_dwordx4 v[112:115], v[112:113], off
	v_lshl_add_u64 v[116:117], s[20:21], 0, v[138:139]
	s_waitcnt vmcnt(10) lgkmcnt(0)
	v_mfma_f32_16x16x32_bf16 v[172:175], v[176:179], v[52:55], v[172:175]
	ds_read_b128 v[176:179], v156 offset:192
	ds_read_b128 v[184:187], v156 offset:16960
	global_load_dwordx4 v[116:119], v[116:117], off
	v_lshl_add_u64 v[120:121], s[20:21], 0, v[140:141]
	global_load_dwordx4 v[120:123], v[120:121], off
	s_waitcnt vmcnt(11) lgkmcnt(1)
	v_mfma_f32_16x16x32_bf16 v[172:175], v[176:179], v[48:51], v[172:175]
	ds_read_b128 v[176:179], v156 offset:256
	ds_read_b128 v[188:191], v156 offset:25408
	v_lshl_add_u64 v[124:125], s[20:21], 0, v[142:143]
	global_load_dwordx4 v[124:127], v[124:125], off
	s_waitcnt vmcnt(11) lgkmcnt(1)
	v_mfma_f32_16x16x32_bf16 v[172:175], v[176:179], v[44:47], v[172:175]
	ds_read_b128 v[176:179], v156 offset:320
	s_add_i32 s17, s17, 16
	s_add_i32 s16, s16, 1
	s_waitcnt vmcnt(10) lgkmcnt(0)
	v_mfma_f32_16x16x32_bf16 v[172:175], v[176:179], v[40:43], v[172:175]
	ds_read_b128 v[176:179], v156 offset:384
	v_lshl_add_u64 v[136:137], v[136:137], 0, s[12:13]
	v_lshl_add_u64 v[138:139], v[138:139], 0, s[12:13]
	s_waitcnt vmcnt(9) lgkmcnt(0)
	v_mfma_f32_16x16x32_bf16 v[172:175], v[176:179], v[36:39], v[172:175]
	ds_read_b128 v[176:179], v156 offset:448
	v_lshl_add_u64 v[140:141], v[140:141], 0, s[12:13]
	v_lshl_add_u64 v[142:143], v[142:143], 0, s[12:13]
	s_waitcnt vmcnt(8) lgkmcnt(0)
	v_mfma_f32_16x16x32_bf16 v[172:175], v[176:179], v[32:35], v[172:175]
	ds_read_b128 v[176:179], v156 offset:8448
	v_lshl_add_u64 v[144:145], v[144:145], 0, s[14:15]
	v_lshl_add_u64 v[146:147], v[146:147], 0, s[14:15]
	s_waitcnt lgkmcnt(0)
	v_mfma_f32_16x16x32_bf16 v[176:179], v[176:179], v[60:63], 0
	s_nop 2
	v_max_f32_e32 v171, v172, v172
	v_lshl_add_u64 v[148:149], v[148:149], 0, s[14:15]
	v_lshl_add_u64 v[150:151], v[150:151], 0, s[14:15]
	v_mfma_f32_16x16x32_bf16 v[176:179], v[180:183], v[56:59], v[176:179]
	ds_read_b128 v[180:183], v156 offset:8576
	s_cmp_lg_u32 s16, 4
	s_waitcnt lgkmcnt(0)
	v_mfma_f32_16x16x32_bf16 v[176:179], v[180:183], v[52:55], v[176:179]
	ds_read_b128 v[180:183], v156 offset:8640
	s_waitcnt lgkmcnt(0)
	v_mfma_f32_16x16x32_bf16 v[176:179], v[180:183], v[48:51], v[176:179]
	ds_read_b128 v[180:183], v156 offset:8704
	s_waitcnt lgkmcnt(0)
	v_mfma_f32_16x16x32_bf16 v[176:179], v[180:183], v[44:47], v[176:179]
	ds_read_b128 v[180:183], v156 offset:8768
	s_waitcnt lgkmcnt(0)
	v_mfma_f32_16x16x32_bf16 v[176:179], v[180:183], v[40:43], v[176:179]
	ds_read_b128 v[180:183], v156 offset:8832
	s_waitcnt lgkmcnt(0)
	v_mfma_f32_16x16x32_bf16 v[176:179], v[180:183], v[36:39], v[176:179]
	ds_read_b128 v[180:183], v156 offset:8896
	s_waitcnt lgkmcnt(0)
	v_mfma_f32_16x16x32_bf16 v[176:179], v[180:183], v[32:35], v[176:179]
	ds_read_b128 v[180:183], v156 offset:16896
	s_waitcnt lgkmcnt(0)
	v_mfma_f32_16x16x32_bf16 v[180:183], v[180:183], v[60:63], 0
	v_mfma_f32_16x16x32_bf16 v[180:183], v[184:187], v[56:59], v[180:183]
	ds_read_b128 v[184:187], v156 offset:17024
	s_waitcnt lgkmcnt(0)
	v_mfma_f32_16x16x32_bf16 v[180:183], v[184:187], v[52:55], v[180:183]
	ds_read_b128 v[184:187], v156 offset:17088
	s_waitcnt lgkmcnt(0)
	v_mfma_f32_16x16x32_bf16 v[180:183], v[184:187], v[48:51], v[180:183]
	ds_read_b128 v[184:187], v156 offset:17152
	s_waitcnt lgkmcnt(0)
	v_mfma_f32_16x16x32_bf16 v[180:183], v[184:187], v[44:47], v[180:183]
	ds_read_b128 v[184:187], v156 offset:17216
	s_waitcnt lgkmcnt(0)
	v_mfma_f32_16x16x32_bf16 v[180:183], v[184:187], v[40:43], v[180:183]
	ds_read_b128 v[184:187], v156 offset:17280
	s_waitcnt lgkmcnt(0)
	v_mfma_f32_16x16x32_bf16 v[180:183], v[184:187], v[36:39], v[180:183]
	ds_read_b128 v[184:187], v156 offset:17344
	s_waitcnt lgkmcnt(0)
	v_mfma_f32_16x16x32_bf16 v[180:183], v[184:187], v[32:35], v[180:183]
	ds_read_b128 v[184:187], v156 offset:25344
	s_waitcnt lgkmcnt(0)
	v_mfma_f32_16x16x32_bf16 v[184:187], v[184:187], v[60:63], 0
	v_mfma_f32_16x16x32_bf16 v[184:187], v[188:191], v[56:59], v[184:187]
	ds_read_b128 v[188:191], v156 offset:25472
	s_waitcnt lgkmcnt(0)
	v_mfma_f32_16x16x32_bf16 v[184:187], v[188:191], v[52:55], v[184:187]
	ds_read_b128 v[188:191], v156 offset:25536
	s_waitcnt lgkmcnt(0)
	v_mfma_f32_16x16x32_bf16 v[184:187], v[188:191], v[48:51], v[184:187]
	ds_read_b128 v[188:191], v156 offset:25600
	s_waitcnt lgkmcnt(0)
	v_mfma_f32_16x16x32_bf16 v[184:187], v[188:191], v[44:47], v[184:187]
	ds_read_b128 v[188:191], v156 offset:25664
	s_waitcnt lgkmcnt(0)
	v_mfma_f32_16x16x32_bf16 v[184:187], v[188:191], v[40:43], v[184:187]
	ds_read_b128 v[188:191], v156 offset:25728
	s_waitcnt lgkmcnt(0)
; #define LAS __attribute__((address_space(3)))
; DEVINL unsigned cvt_pk_bf16(float lo, float hi) { const f32x2 v = {lo, hi}; return __builtin_bit_cast(unsigned, __builtin_convertvector(v, bf16x2_t)); }
; template <int DQK, int D1, int DV, bool MLA, int NQ>
; DEVINL void attn_block(LAS unsigned char* lds, const bf16_t* q, int ldq, const bf16_t* k1, int ld1, const bf16_t* k2, int ld2,
;                        const bf16_t* vt, int ldv, bf16_t* o, int ldo, int nt, int qtile0, const f32x2* cs, float sc) {
;     ...
;             for (int qi = 0; qi < NQ; ++qi) {
;                 float mx = s[qi][0][0];
; #pragma unroll
;                 for (int kb = 0; kb < 4; ++kb)
; #pragma unroll
;                     for (int i = 0; i < 4; ++i) mx = fmaxf(mx, s[qi][kb][i]);
;                 mx = fmaxf(mx, __shfl_xor(mx, 16)); mx = fmaxf(mx, __shfl_xor(mx, 32));
;                 const float mnew = fmaxf(mrun[qi], mx * sc), alpha = __builtin_amdgcn_exp2f(mrun[qi] - mnew);
;                 mrun[qi] = mnew; float ls = 0.f;
; #pragma unroll
;                 for (int kb = 0; kb < 4; ++kb)
; #pragma unroll
;                     for (int i = 0; i < 4; ++i) { const float p = __builtin_amdgcn_exp2f(s[qi][kb][i] * sc - mnew); s[qi][kb][i] = p; ls += p; }
;                 lrun[qi] = lrun[qi] * alpha + ls;
; #pragma unroll
;                 for (int i = 0; i < NDB; ++i) acc[qi][i] *= alpha;
; #pragma unroll
;                 for (int ks = 0; ks < 2; ++ks) { u32x4 pw; pw.x = cvt_pk_bf16(s[qi][2 * ks][0], s[qi][2 * ks][1]); pw.y = cvt_pk_bf16(s[qi][2 * ks][2], s[qi][2 * ks][3]); pw.z = cvt_pk_bf16(s[qi][2 * ks + 1][0], s[qi][2 * ks + 1][1]); pw.w = cvt_pk_bf16(s[qi][2 * ks + 1][2], s[qi][2 * ks + 1][3]);
;                     pf[qi][ks] = __builtin_bit_cast(bf16x8, pw); }
;             }
; #pragma unroll
;             for (int ks = 0; ks < 2; ++ks)
; #pragma unroll
;                 for (int db = 0; db < NDB; ++db) { const LAS unsigned char* vp = cb + 64 * KS + (db * 16 + fr) * VS + (32 * ks + 4 * fq) * 2;
;                     const u32x2 lo = *(const LAS u32x2*)vp, hi = *(const LAS u32x2*)(vp + 32);
;                     const bf16x8 a = __builtin_bit_cast(bf16x8, (u32x4){lo.x, lo.y, hi.x, hi.y});
; #pragma unroll
;                     for (int qi = 0; qi < NQ; ++qi) acc[qi][db] = __builtin_amdgcn_mfma_f32_16x16x32_bf16(a, pf[qi][ks], acc[qi][db], 0, 0, 0); }
	v_mfma_f32_16x16x32_bf16 v[184:187], v[188:191], v[36:39], v[184:187]
	ds_read_b128 v[188:191], v156 offset:25792
	v_max_f32_e32 v156, v173, v173
	v_max_f32_e32 v156, v171, v156
	v_max3_f32 v156, v156, v174, v175
	s_waitcnt lgkmcnt(0)
	v_mfma_f32_16x16x32_bf16 v[184:187], v[188:191], v[32:35], v[184:187]
	v_max3_f32 v156, v156, v176, v177
	v_max3_f32 v156, v156, v178, v179
	v_max3_f32 v156, v156, v180, v181
	v_max3_f32 v156, v156, v182, v183
	s_nop 3
	v_max3_f32 v156, v156, v184, v185
	v_max3_f32 v156, v156, v186, v187
	v_mov_b32_e32 v171, v156
	s_nop 1
	v_permlane16_swap_b32_e32 v156, v171
	v_max_f32_e32 v156, v156, v171
	v_mov_b32_e32 v171, v156
	s_nop 1
	v_permlane32_swap_b32_e32 v156, v171
	v_max_f32_e32 v156, v156, v171
	v_mul_f32_e32 v156, 0x3db8aa3b, v156
	v_max_f32_e32 v171, v192, v192
	v_max_f32_e32 v171, v171, v156
	v_sub_f32_e32 v156, v192, v171
	v_exp_f32_e32 v188, v156
	v_fma_f32 v156, v172, s38, -v171
	v_exp_f32_e32 v172, v156
	v_fma_f32 v173, v173, s38, -v171
	v_exp_f32_e32 v173, v173
	v_fma_f32 v174, v174, s38, -v171
	v_exp_f32_e32 v174, v174
	v_fma_f32 v175, v175, s38, -v171
	v_exp_f32_e32 v175, v175
	v_fma_f32 v176, v176, s38, -v171
	v_add_f32_e32 v156, 0, v172
	v_exp_f32_e32 v176, v176
	v_fma_f32 v177, v177, s38, -v171
	v_add_f32_e32 v156, v173, v156
	v_exp_f32_e32 v177, v177
	v_fma_f32 v178, v178, s38, -v171
	v_add_f32_e32 v156, v174, v156
	v_exp_f32_e32 v178, v178
	v_fma_f32 v179, v179, s38, -v171
	v_add_f32_e32 v156, v175, v156
	v_exp_f32_e32 v179, v179
	v_fma_f32 v180, v180, s38, -v171
	v_add_f32_e32 v156, v176, v156
	v_exp_f32_e32 v180, v180
	v_fma_f32 v181, v181, s38, -v171
	v_add_f32_e32 v156, v177, v156
	v_exp_f32_e32 v181, v181
	v_fma_f32 v182, v182, s38, -v171
	v_add_f32_e32 v156, v178, v156
	v_exp_f32_e32 v182, v182
	v_fma_f32 v183, v183, s38, -v171
	v_add_f32_e32 v156, v179, v156
	v_exp_f32_e32 v183, v183
	v_fma_f32 v184, v184, s38, -v171
	v_add_f32_e32 v156, v180, v156
	v_exp_f32_e32 v184, v184
	v_fma_f32 v185, v185, s38, -v171
	v_add_f32_e32 v156, v181, v156
	v_exp_f32_e32 v185, v185
	v_fma_f32 v186, v186, s38, -v171
	v_fma_f32 v187, v187, s38, -v171
	v_add_f32_e32 v156, v182, v156
	v_exp_f32_e32 v186, v186
	v_exp_f32_e32 v187, v187
	v_add_f32_e32 v156, v183, v156
	v_add_f32_e32 v156, v184, v156
	v_add_f32_e32 v156, v185, v156
	v_cvt_pk_bf16_f32 v172, v172, v173
	v_cvt_pk_bf16_f32 v173, v174, v175
	v_cvt_pk_bf16_f32 v175, v178, v179
	v_cvt_pk_bf16_f32 v178, v184, v185
	v_add3_u32 v184, s24, v132, v157
	v_add_f32_e32 v156, v186, v156
	v_cvt_pk_bf16_f32 v179, v186, v187
	v_add_u32_e32 v186, 0x8000, v184
	v_cvt_pk_bf16_f32 v174, v176, v177
	v_cvt_pk_bf16_f32 v176, v180, v181
	v_cvt_pk_bf16_f32 v177, v182, v183
	ds_read2_b64 v[180:183], v186 offset0:128 offset1:132
	v_pk_mul_f32 v[94:95], v[94:95], v[188:189] op_sel_hi:[1,0]
	v_pk_mul_f32 v[92:93], v[92:93], v[188:189] op_sel_hi:[1,0]
	v_add_f32_e32 v156, v187, v156
	v_add_u32_e32 v187, 0x8800, v184
	s_waitcnt lgkmcnt(0)
	v_mfma_f32_16x16x32_bf16 v[92:95], v[180:183], v[172:175], v[92:95]
	ds_read2_b64 v[180:183], v187 offset0:160 offset1:164
	v_pk_mul_f32 v[90:91], v[90:91], v[188:189] op_sel_hi:[1,0]
	v_pk_mul_f32 v[88:89], v[88:89], v[188:189] op_sel_hi:[1,0]
	v_pk_mul_f32 v[86:87], v[86:87], v[188:189] op_sel_hi:[1,0]
	v_pk_mul_f32 v[84:85], v[84:85], v[188:189] op_sel_hi:[1,0]
	v_pk_mul_f32 v[82:83], v[82:83], v[188:189] op_sel_hi:[1,0]
	v_pk_mul_f32 v[80:81], v[80:81], v[188:189] op_sel_hi:[1,0]
	v_pk_mul_f32 v[78:79], v[78:79], v[188:189] op_sel_hi:[1,0]
	v_pk_mul_f32 v[76:77], v[76:77], v[188:189] op_sel_hi:[1,0]
	v_pk_mul_f32 v[74:75], v[74:75], v[188:189] op_sel_hi:[1,0]
	v_pk_mul_f32 v[72:73], v[72:73], v[188:189] op_sel_hi:[1,0]
	v_pk_mul_f32 v[70:71], v[70:71], v[188:189] op_sel_hi:[1,0]
	v_pk_mul_f32 v[68:69], v[68:69], v[188:189] op_sel_hi:[1,0]
	v_pk_mul_f32 v[66:67], v[66:67], v[188:189] op_sel_hi:[1,0]
	v_pk_mul_f32 v[64:65], v[64:65], v[188:189] op_sel_hi:[1,0]
	v_pk_mul_f32 v[30:31], v[30:31], v[188:189] op_sel_hi:[1,0]
	v_pk_mul_f32 v[28:29], v[28:29], v[188:189] op_sel_hi:[1,0]
	v_pk_mul_f32 v[26:27], v[26:27], v[188:189] op_sel_hi:[1,0]
	v_pk_mul_f32 v[24:25], v[24:25], v[188:189] op_sel_hi:[1,0]
	v_pk_mul_f32 v[22:23], v[22:23], v[188:189] op_sel_hi:[1,0]
	v_pk_mul_f32 v[20:21], v[20:21], v[188:189] op_sel_hi:[1,0]
	v_pk_mul_f32 v[18:19], v[18:19], v[188:189] op_sel_hi:[1,0]
	v_pk_mul_f32 v[16:17], v[16:17], v[188:189] op_sel_hi:[1,0]
	v_pk_mul_f32 v[14:15], v[14:15], v[188:189] op_sel_hi:[1,0]
	v_pk_mul_f32 v[12:13], v[12:13], v[188:189] op_sel_hi:[1,0]
	v_pk_mul_f32 v[10:11], v[10:11], v[188:189] op_sel_hi:[1,0]
	v_pk_mul_f32 v[8:9], v[8:9], v[188:189] op_sel_hi:[1,0]
	v_pk_mul_f32 v[6:7], v[6:7], v[188:189] op_sel_hi:[1,0]
	v_pk_mul_f32 v[4:5], v[4:5], v[188:189] op_sel_hi:[1,0]
	v_pk_mul_f32 v[2:3], v[2:3], v[188:189] op_sel_hi:[1,0]
	v_pk_mul_f32 v[0:1], v[0:1], v[188:189] op_sel_hi:[1,0]
	v_add_u32_e32 v189, 0x9000, v184
	s_waitcnt lgkmcnt(0)
	v_mfma_f32_16x16x32_bf16 v[88:91], v[180:183], v[172:175], v[88:91]
	ds_read2_b64 v[180:183], v189 offset0:192 offset1:196
	v_add_u32_e32 v190, 0x9800, v184
	v_add_u32_e32 v191, 0xa800, v184
	s_waitcnt lgkmcnt(0)
	v_mfma_f32_16x16x32_bf16 v[84:87], v[180:183], v[172:175], v[84:87]
	ds_read2_b64 v[180:183], v190 offset0:224 offset1:228
	v_add_u32_e32 v192, 0xb000, v184
	v_add_u32_e32 v194, 0xb800, v184
	s_waitcnt lgkmcnt(0)
	v_mfma_f32_16x16x32_bf16 v[80:83], v[180:183], v[172:175], v[80:83]
	ds_read2_b64 v[180:183], v191 offset1:4
	v_add_u32_e32 v195, 0xc000, v184
	v_add_u32_e32 v196, 0xc800, v184
	s_waitcnt lgkmcnt(0)
; #define LAS __attribute__((address_space(3)))
; template <int DQK, int D1, int DV, bool MLA, int NQ>
; DEVINL void attn_block(LAS unsigned char* lds, const bf16_t* q, int ldq, const bf16_t* k1, int ld1, const bf16_t* k2, int ld2,
;                        const bf16_t* vt, int ldv, bf16_t* o, int ldo, int nt, int qtile0, const f32x2* cs, float sc) {
;     ...
;         for (int i = 0; i < NC1; ++i) { const int c = tid + i * 512, row = c / CPR1, cc = c % CPR1; *(LAS u32x4*)(b + row * KS + cc * 16) = r1[i]; }
;         if (D2 > 0) { const int row = tid >> 3, cc = tid & 7; *(LAS u32x4*)(b + row * KS + D1 * 2 + cc * 16) = r2; }
; #pragma unroll
;         for (int i = 0; i < NCV; ++i) { const int c = tid + i * 512, row = c >> 3, cc = c & 7; *(LAS u32x4*)(b + 64 * KS + row * VS + cc * 16) = rv[i]; }
;     ...
;             for (int ks = 0; ks < 2; ++ks)
; #pragma unroll
;                 for (int db = 0; db < NDB; ++db) { const LAS unsigned char* vp = cb + 64 * KS + (db * 16 + fr) * VS + (32 * ks + 4 * fq) * 2;
;                     const u32x2 lo = *(const LAS u32x2*)vp, hi = *(const LAS u32x2*)(vp + 32);
;                     const bf16x8 a = __builtin_bit_cast(bf16x8, (u32x4){lo.x, lo.y, hi.x, hi.y});
; #pragma unroll
;                     for (int qi = 0; qi < NQ; ++qi) acc[qi][db] = __builtin_amdgcn_mfma_f32_16x16x32_bf16(a, pf[qi][ks], acc[qi][db], 0, 0, 0); }
;         }
;         if (j + 1 < nt) lstore(lds + ((j + 1) & 1) * BUF);
;         __syncthreads();
	v_mfma_f32_16x16x32_bf16 v[76:79], v[180:183], v[172:175], v[76:79]
	ds_read2_b64 v[180:183], v192 offset0:32 offset1:36
	v_add_u32_e32 v197, 0xd000, v184
	v_add_u32_e32 v198, 0xd800, v184
	s_waitcnt lgkmcnt(0)
	v_mfma_f32_16x16x32_bf16 v[72:75], v[180:183], v[172:175], v[72:75]
	ds_read2_b64 v[180:183], v194 offset0:64 offset1:68
	v_add_u32_e32 v199, 0xe000, v184
	v_add_u32_e32 v200, 0xf000, v184
	s_waitcnt lgkmcnt(0)
	v_mfma_f32_16x16x32_bf16 v[68:71], v[180:183], v[172:175], v[68:71]
	ds_read2_b64 v[180:183], v195 offset0:96 offset1:100
	v_add_u32_e32 v201, 0xf800, v184
	v_add_u32_e32 v185, 0x8400, v184
	s_waitcnt lgkmcnt(0)
	v_mfma_f32_16x16x32_bf16 v[64:67], v[180:183], v[172:175], v[64:67]
	ds_read2_b64 v[180:183], v196 offset0:128 offset1:132
	v_fmac_f32_e32 v156, v193, v188
	s_waitcnt lgkmcnt(0)
	v_mfma_f32_16x16x32_bf16 v[28:31], v[180:183], v[172:175], v[28:31]
	ds_read2_b64 v[180:183], v197 offset0:160 offset1:164
	s_waitcnt lgkmcnt(0)
	v_mfma_f32_16x16x32_bf16 v[24:27], v[180:183], v[172:175], v[24:27]
	ds_read2_b64 v[180:183], v198 offset0:192 offset1:196
	s_waitcnt lgkmcnt(0)
	v_mfma_f32_16x16x32_bf16 v[20:23], v[180:183], v[172:175], v[20:23]
	ds_read2_b64 v[180:183], v199 offset0:224 offset1:228
	s_waitcnt lgkmcnt(0)
	v_mfma_f32_16x16x32_bf16 v[16:19], v[180:183], v[172:175], v[16:19]
	ds_read2_b64 v[180:183], v200 offset1:4
	s_waitcnt lgkmcnt(0)
	v_mfma_f32_16x16x32_bf16 v[12:15], v[180:183], v[172:175], v[12:15]
	ds_read2_b64 v[180:183], v201 offset0:32 offset1:36
	s_waitcnt lgkmcnt(0)
	v_mfma_f32_16x16x32_bf16 v[8:11], v[180:183], v[172:175], v[8:11]
	v_add_u32_e32 v180, 0x7800, v185
	ds_read2_b64 v[180:183], v180 offset0:192 offset1:196
	s_waitcnt lgkmcnt(0)
	v_mfma_f32_16x16x32_bf16 v[4:7], v[180:183], v[172:175], v[4:7]
	v_add_u32_e32 v180, 0x8000, v185
	ds_read2_b64 v[180:183], v180 offset0:224 offset1:228
	s_waitcnt lgkmcnt(0)
	v_mfma_f32_16x16x32_bf16 v[0:3], v[180:183], v[172:175], v[0:3]
	ds_read2_b64 v[172:175], v186 offset0:136 offset1:140
	v_add_u32_e32 v180, 0x8440, v184
	s_waitcnt lgkmcnt(0)
	v_mfma_f32_16x16x32_bf16 v[92:95], v[172:175], v[176:179], v[92:95]
	ds_read2_b64 v[172:175], v187 offset0:168 offset1:172
	s_waitcnt lgkmcnt(0)
	v_mfma_f32_16x16x32_bf16 v[88:91], v[172:175], v[176:179], v[88:91]
	ds_read2_b64 v[172:175], v189 offset0:200 offset1:204
	s_waitcnt lgkmcnt(0)
	v_mfma_f32_16x16x32_bf16 v[84:87], v[172:175], v[176:179], v[84:87]
	ds_read2_b64 v[172:175], v190 offset0:232 offset1:236
	s_waitcnt lgkmcnt(0)
	v_mfma_f32_16x16x32_bf16 v[80:83], v[172:175], v[176:179], v[80:83]
	ds_read2_b64 v[172:175], v191 offset0:8 offset1:12
	s_waitcnt lgkmcnt(0)
	v_mfma_f32_16x16x32_bf16 v[76:79], v[172:175], v[176:179], v[76:79]
	ds_read2_b64 v[172:175], v192 offset0:40 offset1:44
	s_waitcnt lgkmcnt(0)
	v_mfma_f32_16x16x32_bf16 v[72:75], v[172:175], v[176:179], v[72:75]
	ds_read2_b64 v[172:175], v194 offset0:72 offset1:76
	s_waitcnt lgkmcnt(0)
	v_mfma_f32_16x16x32_bf16 v[68:71], v[172:175], v[176:179], v[68:71]
	ds_read2_b64 v[172:175], v195 offset0:104 offset1:108
	s_waitcnt lgkmcnt(0)
	v_mfma_f32_16x16x32_bf16 v[64:67], v[172:175], v[176:179], v[64:67]
	ds_read2_b64 v[172:175], v196 offset0:136 offset1:140
	s_waitcnt lgkmcnt(0)
	v_mfma_f32_16x16x32_bf16 v[28:31], v[172:175], v[176:179], v[28:31]
	ds_read2_b64 v[172:175], v197 offset0:168 offset1:172
	s_waitcnt lgkmcnt(0)
	v_mfma_f32_16x16x32_bf16 v[24:27], v[172:175], v[176:179], v[24:27]
	ds_read2_b64 v[172:175], v198 offset0:200 offset1:204
	s_waitcnt lgkmcnt(0)
	v_mfma_f32_16x16x32_bf16 v[20:23], v[172:175], v[176:179], v[20:23]
	ds_read2_b64 v[172:175], v199 offset0:232 offset1:236
	s_waitcnt lgkmcnt(0)
	v_mfma_f32_16x16x32_bf16 v[16:19], v[172:175], v[176:179], v[16:19]
	ds_read2_b64 v[172:175], v200 offset0:8 offset1:12
	s_waitcnt lgkmcnt(0)
	v_mfma_f32_16x16x32_bf16 v[12:15], v[172:175], v[176:179], v[12:15]
	ds_read2_b64 v[172:175], v201 offset0:40 offset1:44
	s_waitcnt lgkmcnt(0)
	v_mfma_f32_16x16x32_bf16 v[8:11], v[172:175], v[176:179], v[8:11]
	v_add_u32_e32 v172, 0x7800, v180
	ds_read2_b64 v[172:175], v172 offset0:192 offset1:196
	s_waitcnt lgkmcnt(0)
	v_mfma_f32_16x16x32_bf16 v[4:7], v[172:175], v[176:179], v[4:7]
	v_add_u32_e32 v172, 0x8000, v180
	ds_read2_b64 v[172:175], v172 offset0:224 offset1:228
	s_waitcnt lgkmcnt(0)
	v_mfma_f32_16x16x32_bf16 v[0:3], v[172:175], v[176:179], v[0:3]
	v_add3_u32 v172, s17, v158, v159
	s_waitcnt vmcnt(7)
	ds_write_b128 v172, v[96:99]
	v_add3_u32 v96, s17, v160, v161
	s_waitcnt vmcnt(6)
	ds_write_b128 v96, v[100:103]
	v_add3_u32 v96, s17, v162, v163
	s_waitcnt vmcnt(5)
	ds_write_b128 v96, v[104:107]
	v_add3_u32 v96, s17, v164, v165
	s_waitcnt vmcnt(4)
	ds_write_b128 v96, v[108:111]
	v_add3_u32 v96, s17, v166, v134
	s_waitcnt vmcnt(3)
	ds_write_b128 v96, v[112:115] offset:33792
	v_add3_u32 v96, s17, v167, v134
	s_waitcnt vmcnt(2)
	ds_write_b128 v96, v[116:119] offset:33792
	v_add3_u32 v96, s17, v168, v134
	s_waitcnt vmcnt(1)
	ds_write_b128 v96, v[120:123] offset:33792
	v_add3_u32 v96, s17, v169, v134
	s_waitcnt vmcnt(0)
	ds_write_b128 v96, v[124:127] offset:33792
	s_waitcnt lgkmcnt(0)
	s_barrier
	s_cbranch_scc1 .LBB0_1552
; #define LAS __attribute__((address_space(3)))
; template <int DQK, int D1, int DV, bool MLA, int NQ>
; DEVINL void attn_block(LAS unsigned char* lds, const bf16_t* q, int ldq, const bf16_t* k1, int ld1, const bf16_t* k2, int ld2,
;                        const bf16_t* vt, int ldv, bf16_t* o, int ldo, int nt, int qtile0, const f32x2* cs, float sc) {
;     ...
;         if (j <= jmax) {
;             f32x4 s[NQ][4];
; #pragma unroll
;             for (int kb = 0; kb < 4; ++kb) {
; #pragma unroll
;                 for (int qi = 0; qi < NQ; ++qi) s[qi][kb] = (f32x4){0.f, 0.f, 0.f, 0.f};
; #pragma unroll
;                 for (int ks = 0; ks < NKS; ++ks) { const bf16x8 a = *(const LAS bf16x8*)(cb + (kb * 16 + fr) * KS + ks * 64 + fq * 16);
; #pragma unroll
;                     for (int qi = 0; qi < NQ; ++qi) s[qi][kb] = __builtin_amdgcn_mfma_f32_16x16x32_bf16(a, qf[qi][ks], s[qi][kb], 0, 0, 0); } }
	v_add3_u32 v116, s40, v128, v170
	ds_read_b128 v[96:99], v116
	ds_read_b128 v[100:103], v116 offset:64
	ds_read_b128 v[104:107], v116 offset:8448
	ds_read_b128 v[108:111], v116 offset:8512
	ds_read_b128 v[112:115], v116 offset:128
	s_add_u32 s6, s54, s6
	s_waitcnt lgkmcnt(4)
	v_mfma_f32_16x16x32_bf16 v[96:99], v[96:99], v[60:63], 0
	s_addc_u32 s7, s55, s7
	s_lshl_b32 s16, s41, 1
	s_add_u32 s6, s6, s16
	s_waitcnt lgkmcnt(3)
	v_mfma_f32_16x16x32_bf16 v[96:99], v[100:103], v[56:59], v[96:99]
	ds_read_b128 v[100:103], v116 offset:192
	s_addc_u32 s7, s7, 0
	s_waitcnt lgkmcnt(1)
	v_mfma_f32_16x16x32_bf16 v[96:99], v[112:115], v[52:55], v[96:99]
	ds_read_b128 v[112:115], v116 offset:256
	v_mfma_f32_16x16x32_bf16 v[104:107], v[104:107], v[60:63], 0
	s_waitcnt lgkmcnt(1)
	v_mfma_f32_16x16x32_bf16 v[96:99], v[100:103], v[48:51], v[96:99]
	ds_read_b128 v[100:103], v116 offset:320
	s_waitcnt lgkmcnt(1)
	v_mfma_f32_16x16x32_bf16 v[96:99], v[112:115], v[44:47], v[96:99]
	ds_read_b128 v[112:115], v116 offset:384
	s_waitcnt lgkmcnt(1)
	v_mfma_f32_16x16x32_bf16 v[96:99], v[100:103], v[40:43], v[96:99]
	ds_read_b128 v[100:103], v116 offset:448
	s_waitcnt lgkmcnt(1)
	v_mfma_f32_16x16x32_bf16 v[96:99], v[112:115], v[36:39], v[96:99]
	ds_read_b128 v[112:115], v116 offset:17024
	s_waitcnt lgkmcnt(1)
	v_mfma_f32_16x16x32_bf16 v[96:99], v[100:103], v[32:35], v[96:99]
	ds_read_b128 v[100:103], v116 offset:8576
	v_mfma_f32_16x16x32_bf16 v[104:107], v[108:111], v[56:59], v[104:107]
	ds_read_b128 v[108:111], v116 offset:8640
	s_waitcnt lgkmcnt(1)
	v_mfma_f32_16x16x32_bf16 v[100:103], v[100:103], v[52:55], v[104:107]
	s_nop 4
	ds_read_b128 v[104:107], v116 offset:8704
	s_waitcnt lgkmcnt(1)
	v_mfma_f32_16x16x32_bf16 v[100:103], v[108:111], v[48:51], v[100:103]
	ds_read_b128 v[108:111], v116 offset:8768
	s_waitcnt lgkmcnt(1)
	v_mfma_f32_16x16x32_bf16 v[100:103], v[104:107], v[44:47], v[100:103]
	ds_read_b128 v[104:107], v116 offset:8832
	s_waitcnt lgkmcnt(1)
	v_mfma_f32_16x16x32_bf16 v[100:103], v[108:111], v[40:43], v[100:103]
	ds_read_b128 v[108:111], v116 offset:8896
	s_waitcnt lgkmcnt(1)
	v_mfma_f32_16x16x32_bf16 v[100:103], v[104:107], v[36:39], v[100:103]
	ds_read_b128 v[104:107], v116 offset:16896
	s_waitcnt lgkmcnt(1)
	v_mfma_f32_16x16x32_bf16 v[100:103], v[108:111], v[32:35], v[100:103]
	ds_read_b128 v[108:111], v116 offset:16960
	s_waitcnt lgkmcnt(1)
	v_mfma_f32_16x16x32_bf16 v[104:107], v[104:107], v[60:63], 0
	s_waitcnt lgkmcnt(0)
	v_mfma_f32_16x16x32_bf16 v[104:107], v[108:111], v[56:59], v[104:107]
	ds_read_b128 v[108:111], v116 offset:17088
	v_mfma_f32_16x16x32_bf16 v[104:107], v[112:115], v[52:55], v[104:107]
	ds_read_b128 v[112:115], v116 offset:17152
	s_waitcnt lgkmcnt(1)
	v_mfma_f32_16x16x32_bf16 v[104:107], v[108:111], v[48:51], v[104:107]
	ds_read_b128 v[108:111], v116 offset:17216
	s_waitcnt lgkmcnt(1)
	v_mfma_f32_16x16x32_bf16 v[104:107], v[112:115], v[44:47], v[104:107]
	ds_read_b128 v[112:115], v116 offset:17280
	s_waitcnt lgkmcnt(1)
	v_mfma_f32_16x16x32_bf16 v[104:107], v[108:111], v[40:43], v[104:107]
	ds_read_b128 v[108:111], v116 offset:17344
	s_waitcnt lgkmcnt(1)
	v_mfma_f32_16x16x32_bf16 v[104:107], v[112:115], v[36:39], v[104:107]
	ds_read_b128 v[112:115], v116 offset:25344
	s_waitcnt lgkmcnt(1)
	v_mfma_f32_16x16x32_bf16 v[104:107], v[108:111], v[32:35], v[104:107]
	ds_read_b128 v[108:111], v116 offset:25408
	s_waitcnt lgkmcnt(1)
	v_mfma_f32_16x16x32_bf16 v[60:63], v[112:115], v[60:63], 0
	ds_read_b128 v[112:115], v116 offset:25472
	s_waitcnt lgkmcnt(1)
	v_mfma_f32_16x16x32_bf16 v[56:59], v[108:111], v[56:59], v[60:63]
	s_nop 4
	ds_read_b128 v[60:63], v116 offset:25536
	s_waitcnt lgkmcnt(1)
	v_mfma_f32_16x16x32_bf16 v[52:55], v[112:115], v[52:55], v[56:59]
	s_nop 2
	ds_read_b128 v[56:59], v116 offset:25600
	s_waitcnt lgkmcnt(1)
	v_mfma_f32_16x16x32_bf16 v[48:51], v[60:63], v[48:51], v[52:55]
	s_nop 2
	ds_read_b128 v[52:55], v116 offset:25664
	ds_read_b128 v[60:63], v116 offset:25728
	s_waitcnt lgkmcnt(2)
	v_mfma_f32_16x16x32_bf16 v[44:47], v[56:59], v[44:47], v[48:51]
	v_max_f32_e32 v56, v97, v97
	v_max_f32_e32 v57, v96, v96
	s_nop 0
	ds_read_b128 v[48:51], v116 offset:25792
	s_waitcnt lgkmcnt(2)
	v_mfma_f32_16x16x32_bf16 v[40:43], v[52:55], v[40:43], v[44:47]
	s_waitcnt lgkmcnt(1)
	v_mfma_f32_16x16x32_bf16 v[36:39], v[60:63], v[36:39], v[40:43]
	s_nop 0
	v_max_f32_e32 v44, v57, v56
	v_max3_f32 v44, v44, v98, v99
	v_max3_f32 v44, v44, v100, v101
	s_waitcnt lgkmcnt(0)
; #define LAS __attribute__((address_space(3)))
; DEVINL unsigned cvt_pk_bf16(float lo, float hi) { const f32x2 v = {lo, hi}; return __builtin_bit_cast(unsigned, __builtin_convertvector(v, bf16x2_t)); }
; template <int DQK, int D1, int DV, bool MLA, int NQ>
; DEVINL void attn_block(LAS unsigned char* lds, const bf16_t* q, int ldq, const bf16_t* k1, int ld1, const bf16_t* k2, int ld2,
;                        const bf16_t* vt, int ldv, bf16_t* o, int ldo, int nt, int qtile0, const f32x2* cs, float sc) {
;     ...
;             for (int qi = 0; qi < NQ; ++qi) {
;                 float mx = s[qi][0][0];
; #pragma unroll
;                 for (int kb = 0; kb < 4; ++kb)
; #pragma unroll
;                     for (int i = 0; i < 4; ++i) mx = fmaxf(mx, s[qi][kb][i]);
;                 mx = fmaxf(mx, __shfl_xor(mx, 16)); mx = fmaxf(mx, __shfl_xor(mx, 32));
;                 const float mnew = fmaxf(mrun[qi], mx * sc), alpha = __builtin_amdgcn_exp2f(mrun[qi] - mnew);
;                 mrun[qi] = mnew; float ls = 0.f;
; #pragma unroll
;                 for (int kb = 0; kb < 4; ++kb)
; #pragma unroll
;                     for (int i = 0; i < 4; ++i) { const float p = __builtin_amdgcn_exp2f(s[qi][kb][i] * sc - mnew); s[qi][kb][i] = p; ls += p; }
;                 lrun[qi] = lrun[qi] * alpha + ls;
; #pragma unroll
;                 for (int i = 0; i < NDB; ++i) acc[qi][i] *= alpha;
; #pragma unroll
;                 for (int ks = 0; ks < 2; ++ks) { u32x4 pw; pw.x = cvt_pk_bf16(s[qi][2 * ks][0], s[qi][2 * ks][1]); pw.y = cvt_pk_bf16(s[qi][2 * ks][2], s[qi][2 * ks][3]); pw.z = cvt_pk_bf16(s[qi][2 * ks + 1][0], s[qi][2 * ks + 1][1]); pw.w = cvt_pk_bf16(s[qi][2 * ks + 1][2], s[qi][2 * ks + 1][3]);
;                     pf[qi][ks] = __builtin_bit_cast(bf16x8, pw); }
;             }
; #pragma unroll
;             for (int ks = 0; ks < 2; ++ks)
; #pragma unroll
;                 for (int db = 0; db < NDB; ++db) { const LAS unsigned char* vp = cb + 64 * KS + (db * 16 + fr) * VS + (32 * ks + 4 * fq) * 2;
;                     const u32x2 lo = *(const LAS u32x2*)vp, hi = *(const LAS u32x2*)(vp + 32);
;                     const bf16x8 a = __builtin_bit_cast(bf16x8, (u32x4){lo.x, lo.y, hi.x, hi.y});
; #pragma unroll
;                     for (int qi = 0; qi < NQ; ++qi) acc[qi][db] = __builtin_amdgcn_mfma_f32_16x16x32_bf16(a, pf[qi][ks], acc[qi][db], 0, 0, 0); }
	v_mfma_f32_16x16x32_bf16 v[34:37], v[48:51], v[32:35], v[36:39]
	v_max3_f32 v40, v44, v102, v103
	v_max3_f32 v40, v40, v104, v105
	v_max3_f32 v40, v40, v106, v107
	s_nop 4
	v_max3_f32 v32, v40, v34, v35
	v_max3_f32 v32, v32, v36, v37
	v_mov_b32_e32 v33, v32
	s_nop 1
	v_permlane16_swap_b32_e32 v32, v33
	v_max_f32_e32 v32, v32, v33
	v_mov_b32_e32 v33, v32
	s_nop 1
	v_permlane32_swap_b32_e32 v32, v33
	v_max_f32_e32 v32, v32, v33
	v_mul_f32_e32 v32, 0x3db8aa3b, v32
	v_max_f32_e32 v33, v171, v171
	v_max_f32_e32 v33, v33, v32
	v_fma_f32 v38, v96, s38, -v33
	v_exp_f32_e32 v96, v38
	v_fma_f32 v38, v97, s38, -v33
	v_exp_f32_e32 v97, v38
	v_fma_f32 v38, v98, s38, -v33
	v_exp_f32_e32 v98, v38
	v_fma_f32 v38, v99, s38, -v33
	v_exp_f32_e32 v99, v38
	v_fma_f32 v38, v100, s38, -v33
	v_exp_f32_e32 v100, v38
	v_fma_f32 v38, v101, s38, -v33
	v_exp_f32_e32 v101, v38
	v_fma_f32 v38, v102, s38, -v33
	v_exp_f32_e32 v102, v38
	v_fma_f32 v38, v103, s38, -v33
	v_exp_f32_e32 v103, v38
	v_fma_f32 v38, v104, s38, -v33
	v_exp_f32_e32 v104, v38
	v_fma_f32 v38, v105, s38, -v33
	v_fma_f32 v34, v34, s38, -v33
	v_exp_f32_e32 v105, v38
	v_fma_f32 v38, v106, s38, -v33
	v_exp_f32_e32 v108, v34
	v_fma_f32 v34, v35, s38, -v33
	v_sub_f32_e32 v32, v171, v33
	v_exp_f32_e32 v106, v38
	v_fma_f32 v38, v107, s38, -v33
	v_exp_f32_e32 v109, v34
	v_fma_f32 v34, v36, s38, -v33
	v_fma_f32 v33, v37, s38, -v33
	v_exp_f32_e32 v32, v32
	v_exp_f32_e32 v33, v33
	v_exp_f32_e32 v110, v34
	v_exp_f32_e32 v107, v38
	v_pk_mul_f32 v[42:43], v[84:85], v[32:33] op_sel_hi:[1,0]
	v_add3_u32 v84, s39, v132, v157
	v_pk_mul_f32 v[60:61], v[70:71], v[32:33] op_sel_hi:[1,0]
	v_pk_mul_f32 v[58:59], v[68:69], v[32:33] op_sel_hi:[1,0]
	ds_read2_b64 v[68:71], v84 offset1:4
	v_pk_mul_f32 v[36:37], v[94:95], v[32:33] op_sel_hi:[1,0]
	v_pk_mul_f32 v[34:35], v[92:93], v[32:33] op_sel_hi:[1,0]
	v_pk_mul_f32 v[44:45], v[86:87], v[32:33] op_sel_hi:[1,0]
	v_pk_mul_f32 v[56:57], v[74:75], v[32:33] op_sel_hi:[1,0]
	v_pk_mul_f32 v[54:55], v[72:73], v[32:33] op_sel_hi:[1,0]
	v_cvt_pk_bf16_f32 v72, v96, v97
	v_cvt_pk_bf16_f32 v73, v98, v99
	v_add_u32_e32 v85, 0x800, v84
	v_cvt_pk_bf16_f32 v74, v100, v101
	v_cvt_pk_bf16_f32 v75, v102, v103
	v_add_u32_e32 v87, 0x1800, v84
	v_pk_mul_f32 v[52:53], v[78:79], v[32:33] op_sel_hi:[1,0]
	v_pk_mul_f32 v[50:51], v[76:77], v[32:33] op_sel_hi:[1,0]
	ds_read2_b64 v[76:79], v85 offset0:32 offset1:36
	s_waitcnt lgkmcnt(1)
	v_mfma_f32_16x16x32_bf16 v[34:37], v[68:71], v[72:75], v[34:37]
	ds_read2_b64 v[68:71], v87 offset0:96 offset1:100
	v_add_u32_e32 v86, 0x1000, v84
	v_pk_mul_f32 v[40:41], v[90:91], v[32:33] op_sel_hi:[1,0]
	v_pk_mul_f32 v[38:39], v[88:89], v[32:33] op_sel_hi:[1,0]
	v_pk_mul_f32 v[48:49], v[82:83], v[32:33] op_sel_hi:[1,0]
	v_pk_mul_f32 v[46:47], v[80:81], v[32:33] op_sel_hi:[1,0]
	ds_read2_b64 v[80:83], v86 offset0:64 offset1:68
	v_add_u32_e32 v88, 0x2000, v84
	v_add_u32_e32 v90, 0x3000, v84
	s_waitcnt lgkmcnt(2)
	v_mfma_f32_16x16x32_bf16 v[38:41], v[76:79], v[72:75], v[38:41]
	ds_read2_b64 v[76:79], v88 offset0:128 offset1:132
	v_add_u32_e32 v89, 0x2800, v84
	v_add_u32_e32 v91, 0x3800, v84
	s_waitcnt lgkmcnt(2)
	v_mfma_f32_16x16x32_bf16 v[46:49], v[68:71], v[72:75], v[46:49]
	ds_read2_b64 v[68:71], v90 offset0:192 offset1:196
	v_add_u32_e32 v93, 0x5000, v84
	v_add_u32_e32 v92, 0x4800, v84
	s_waitcnt lgkmcnt(2)
	v_mfma_f32_16x16x32_bf16 v[42:45], v[80:83], v[72:75], v[42:45]
	ds_read2_b64 v[80:83], v89 offset0:160 offset1:164
	v_pk_mul_f32 v[66:67], v[66:67], v[32:33] op_sel_hi:[1,0]
	v_pk_mul_f32 v[64:65], v[64:65], v[32:33] op_sel_hi:[1,0]
	s_waitcnt lgkmcnt(2)
	v_mfma_f32_16x16x32_bf16 v[50:53], v[76:79], v[72:75], v[50:53]
	ds_read2_b64 v[76:79], v91 offset0:224 offset1:228
	v_pk_mul_f32 v[26:27], v[26:27], v[32:33] op_sel_hi:[1,0]
	v_pk_mul_f32 v[24:25], v[24:25], v[32:33] op_sel_hi:[1,0]
	s_waitcnt lgkmcnt(2)
	v_mfma_f32_16x16x32_bf16 v[58:61], v[68:71], v[72:75], v[58:61]
	ds_read2_b64 v[68:71], v93 offset0:32 offset1:36
	v_add_u32_e32 v94, 0x5800, v84
	v_add_u32_e32 v111, 0x6800, v84
	s_waitcnt lgkmcnt(2)
	v_mfma_f32_16x16x32_bf16 v[54:57], v[80:83], v[72:75], v[54:57]
	ds_read2_b64 v[80:83], v92 offset1:4
	v_pk_mul_f32 v[30:31], v[30:31], v[32:33] op_sel_hi:[1,0]
	v_pk_mul_f32 v[28:29], v[28:29], v[32:33] op_sel_hi:[1,0]
	s_waitcnt lgkmcnt(2)
	v_mfma_f32_16x16x32_bf16 v[62:65], v[76:79], v[72:75], v[64:67]
	ds_read2_b64 v[76:79], v94 offset0:64 offset1:68
	v_add_u32_e32 v95, 0x6000, v84
	v_pk_mul_f32 v[22:23], v[22:23], v[32:33] op_sel_hi:[1,0]
	s_waitcnt lgkmcnt(2)
	v_mfma_f32_16x16x32_bf16 v[24:27], v[68:71], v[72:75], v[24:27]
	ds_read2_b64 v[66:69], v111 offset0:128 offset1:132
	v_pk_mul_f32 v[20:21], v[20:21], v[32:33] op_sel_hi:[1,0]
	v_pk_mul_f32 v[14:15], v[14:15], v[32:33] op_sel_hi:[1,0]
	s_waitcnt lgkmcnt(2)
	v_mfma_f32_16x16x32_bf16 v[28:31], v[80:83], v[72:75], v[28:31]
	ds_read2_b64 v[80:83], v95 offset0:96 offset1:100
	v_pk_mul_f32 v[12:13], v[12:13], v[32:33] op_sel_hi:[1,0]
	v_add_u32_e32 v112, 0x7000, v84
	v_add_u32_e32 v114, 0x8000, v84
	s_waitcnt lgkmcnt(2)
	v_mfma_f32_16x16x32_bf16 v[20:23], v[76:79], v[72:75], v[20:23]
	ds_read2_b64 v[76:79], v112 offset0:160 offset1:164
	v_pk_mul_f32 v[18:19], v[18:19], v[32:33] op_sel_hi:[1,0]
	v_pk_mul_f32 v[16:17], v[16:17], v[32:33] op_sel_hi:[1,0]
	s_waitcnt lgkmcnt(2)
	v_mfma_f32_16x16x32_bf16 v[12:15], v[66:69], v[72:75], v[12:15]
	ds_read2_b64 v[66:69], v114 offset0:224 offset1:228
	v_add_u32_e32 v113, 0x7800, v84
	v_pk_mul_f32 v[10:11], v[10:11], v[32:33] op_sel_hi:[1,0]
	s_waitcnt lgkmcnt(2)
; #define LAS __attribute__((address_space(3)))
; template <int DQK, int D1, int DV, bool MLA, int NQ>
; DEVINL void attn_block(LAS unsigned char* lds, const bf16_t* q, int ldq, const bf16_t* k1, int ld1, const bf16_t* k2, int ld2,
;                        const bf16_t* vt, int ldv, bf16_t* o, int ldo, int nt, int qtile0, const f32x2* cs, float sc) {
;     ...
;             for (int ks = 0; ks < 2; ++ks)
; #pragma unroll
;                 for (int db = 0; db < NDB; ++db) { const LAS unsigned char* vp = cb + 64 * KS + (db * 16 + fr) * VS + (32 * ks + 4 * fq) * 2;
;                     const u32x2 lo = *(const LAS u32x2*)vp, hi = *(const LAS u32x2*)(vp + 32);
;                     const bf16x8 a = __builtin_bit_cast(bf16x8, (u32x4){lo.x, lo.y, hi.x, hi.y});
; #pragma unroll
;                     for (int qi = 0; qi < NQ; ++qi) acc[qi][db] = __builtin_amdgcn_mfma_f32_16x16x32_bf16(a, pf[qi][ks], acc[qi][db], 0, 0, 0); }
;         }
;         if (j + 1 < nt) lstore(lds + ((j + 1) & 1) * BUF);
;         __syncthreads();
;     }
; #pragma unroll
;     for (int qi = 0; qi < NQ; ++qi) {
;         float l = lrun[qi]; l += __shfl_xor(l, 16); l += __shfl_xor(l, 32);
	v_mfma_f32_16x16x32_bf16 v[16:19], v[80:83], v[72:75], v[16:19]
	v_mul_f32_e64 v8, v8, v32
	v_mul_f32_e64 v9, v9, v32
	ds_read2_b64 v[80:83], v113 offset0:192 offset1:196
	v_pk_mul_f32 v[2:3], v[2:3], v[32:33] op_sel_hi:[1,0]
	v_pk_mul_f32 v[0:1], v[0:1], v[32:33] op_sel_hi:[1,0]
	s_waitcnt lgkmcnt(2)
	v_mfma_f32_16x16x32_bf16 v[8:11], v[76:79], v[72:75], v[8:11]
	ds_read2_b64 v[76:79], v84 offset0:8 offset1:12
	v_pk_mul_f32 v[6:7], v[6:7], v[32:33] op_sel_hi:[1,0]
	v_pk_mul_f32 v[4:5], v[4:5], v[32:33] op_sel_hi:[1,0]
	s_waitcnt lgkmcnt(2)
	v_mfma_f32_16x16x32_bf16 v[0:3], v[66:69], v[72:75], v[0:3]
	ds_read2_b64 v[66:69], v86 offset0:72 offset1:76
	v_cvt_pk_bf16_f32 v70, v104, v105
	v_cvt_pk_bf16_f32 v71, v106, v107
	s_waitcnt lgkmcnt(2)
	v_mfma_f32_16x16x32_bf16 v[4:7], v[80:83], v[72:75], v[4:7]
	v_cvt_pk_bf16_f32 v72, v108, v109
	v_cvt_pk_bf16_f32 v73, v110, v33
	ds_read2_b64 v[80:83], v85 offset0:40 offset1:44
	s_waitcnt lgkmcnt(2)
	v_mfma_f32_16x16x32_bf16 v[34:37], v[76:79], v[70:73], v[34:37]
	ds_read2_b64 v[74:77], v87 offset0:104 offset1:108
	s_waitcnt lgkmcnt(2)
	v_mfma_f32_16x16x32_bf16 v[42:45], v[66:69], v[70:73], v[42:45]
	ds_read2_b64 v[66:69], v88 offset0:136 offset1:140
	s_waitcnt lgkmcnt(1)
	v_mfma_f32_16x16x32_bf16 v[46:49], v[74:77], v[70:73], v[46:49]
	ds_read2_b64 v[74:77], v89 offset0:168 offset1:172
	s_waitcnt lgkmcnt(1)
	v_mfma_f32_16x16x32_bf16 v[50:53], v[66:69], v[70:73], v[50:53]
	ds_read2_b64 v[66:69], v90 offset0:200 offset1:204
	s_waitcnt lgkmcnt(1)
	v_mfma_f32_16x16x32_bf16 v[54:57], v[74:77], v[70:73], v[54:57]
	ds_read2_b64 v[74:77], v91 offset0:232 offset1:236
	s_waitcnt lgkmcnt(1)
	v_mfma_f32_16x16x32_bf16 v[58:61], v[66:69], v[70:73], v[58:61]
	ds_read2_b64 v[66:69], v92 offset0:8 offset1:12
	v_mfma_f32_16x16x32_bf16 v[38:41], v[80:83], v[70:73], v[38:41]
	ds_read2_b64 v[78:81], v94 offset0:72 offset1:76
	s_waitcnt lgkmcnt(2)
	v_mfma_f32_16x16x32_bf16 v[62:65], v[74:77], v[70:73], v[62:65]
	ds_read2_b64 v[74:77], v93 offset0:40 offset1:44
	s_waitcnt lgkmcnt(2)
	v_mfma_f32_16x16x32_bf16 v[28:31], v[66:69], v[70:73], v[28:31]
	ds_read2_b64 v[66:69], v95 offset0:104 offset1:108
	ds_read2_b64 v[82:85], v111 offset0:136 offset1:140
	s_waitcnt lgkmcnt(3)
	v_mfma_f32_16x16x32_bf16 v[20:23], v[78:81], v[70:73], v[20:23]
	v_add_f32_e32 v78, 0, v96
	v_add_f32_e32 v78, v97, v78
	v_add_f32_e32 v78, v98, v78
	s_waitcnt lgkmcnt(1)
	v_mfma_f32_16x16x32_bf16 v[16:19], v[66:69], v[70:73], v[16:19]
	v_add_f32_e32 v66, v99, v78
	v_add_f32_e32 v66, v100, v66
	v_add_f32_e32 v66, v101, v66
	v_add_f32_e32 v66, v102, v66
	v_add_f32_e32 v66, v103, v66
	v_add_f32_e32 v66, v104, v66
	v_add_f32_e32 v66, v105, v66
	v_add_f32_e32 v66, v106, v66
	v_add_f32_e32 v66, v107, v66
	v_add_f32_e32 v66, v108, v66
	v_add_f32_e32 v66, v109, v66
	v_add_f32_e32 v66, v110, v66
	v_add_f32_e32 v33, v33, v66
	v_fmac_f32_e32 v33, v156, v32
	ds_bpermute_b32 v32, v135, v33
	v_mfma_f32_16x16x32_bf16 v[24:27], v[74:77], v[70:73], v[24:27]
	ds_read2_b64 v[74:77], v112 offset0:168 offset1:172
	ds_read2_b64 v[86:89], v113 offset0:200 offset1:204
	ds_read2_b64 v[90:93], v114 offset0:232 offset1:236
	s_waitcnt lgkmcnt(0)
	s_barrier
; DEVINL unsigned cvt_pk_bf16(float lo, float hi) { const f32x2 v = {lo, hi}; return __builtin_bit_cast(unsigned, __builtin_convertvector(v, bf16x2_t)); }
; template <int DQK, int D1, int DV, bool MLA, int NQ>
; DEVINL void attn_block(LAS unsigned char* lds, const bf16_t* q, int ldq, const bf16_t* k1, int ld1, const bf16_t* k2, int ld2,
;                        const bf16_t* vt, int ldv, bf16_t* o, int ldo, int nt, int qtile0, const f32x2* cs, float sc) {
;     ...
; #pragma unroll
;     for (int qi = 0; qi < NQ; ++qi) {
;         float l = lrun[qi]; l += __shfl_xor(l, 16); l += __shfl_xor(l, 32);
;         const float inv = 1.0f / l;
;         bf16_t* orow = o + (size_t)(wid * 16 * NQ + qi * 16 + fr) * ldo + 4 * fq;
; #pragma unroll
;         for (int db = 0; db < NDB; ++db) { u32x2 w; w.x = cvt_pk_bf16(acc[qi][db][0] * inv, acc[qi][db][1] * inv); w.y = cvt_pk_bf16(acc[qi][db][2] * inv, acc[qi][db][3] * inv); *(u32x2*)(orow + db * 16) = w; }
;     }
; DEVINL void mem_attention(LAS unsigned char* lds, const bf16_t* qx, const bf16_t* km, const bf16_t* vtm, bf16_t* o) {
;     ...
;     for (int i = 0; (i * (int)gridDim.x + c) < 1024 && i < 64; ++i) {
;         int bh, qb;
;         if (gridDim.x == 256) { bh = i * 16 + x * 2 + (r >> 4); qb = r & 15; } else { const int uu = i * gridDim.x + c; bh = uu >> 4; qb = uu & 15; }
;         const int b = bh >> 2, h = bh & 3; const size_t t0 = (size_t)b * SEQ + qb * 128;
;         attn_block<256, 256, 256, false, 1>(lds, qx + t0 * 1024 + h * 256, 1024, km + (size_t)(b * 256) * 1024 + h * 256, 1024, nullptr, 0,
;                                             vtm + (size_t)(h * 256) * NMEMT + b * 256, NMEMT, o + t0 * 1024 + h * 256, 1024, 4, 0, nullptr, sc);
	v_add_f32_e32 v32, v33, v32
	ds_bpermute_b32 v33, v133, v32
	v_mfma_f32_16x16x32_bf16 v[12:15], v[82:85], v[70:73], v[12:15]
	v_mov_b32_e32 v133, v129
	s_waitcnt lgkmcnt(0)
	v_add_f32_e32 v66, v32, v33
	v_div_scale_f32 v67, s[16:17], v66, v66, 1.0
	v_rcp_f32_e32 v68, v67
	v_mfma_f32_16x16x32_bf16 v[8:11], v[74:77], v[70:73], v[8:11]
	v_lshl_add_u64 v[32:33], s[6:7], 0, v[130:131]
	v_lshl_add_u64 v[32:33], v[32:33], 0, v[132:133]
	v_fma_f32 v69, -v67, v68, 1.0
	v_fmac_f32_e32 v68, v69, v68
	v_div_scale_f32 v69, vcc, 1.0, v66, 1.0
	v_mfma_f32_16x16x32_bf16 v[4:7], v[86:89], v[70:73], v[4:7]
	s_add_i32 s7, s37, 1
	s_mul_i32 s6, s7, s34
	s_add_i32 s6, s6, s75
	v_mfma_f32_16x16x32_bf16 v[0:3], v[90:93], v[70:73], v[0:3]
	v_mul_f32_e32 v70, v69, v68
	v_fma_f32 v71, -v67, v70, v69
	v_fmac_f32_e32 v70, v71, v68
	v_fma_f32 v67, -v67, v70, v69
	v_div_fmas_f32 v67, v67, v68, v70
	v_div_fixup_f32 v66, v67, v66, 1.0
	v_pk_mul_f32 v[34:35], v[34:35], v[66:67] op_sel_hi:[1,0]
	v_pk_mul_f32 v[36:37], v[36:37], v[66:67] op_sel_hi:[1,0]
	v_cvt_pk_bf16_f32 v34, v34, v35
	v_cvt_pk_bf16_f32 v35, v36, v37
	global_store_dwordx2 v[32:33], v[34:35], off
	v_pk_mul_f32 v[34:35], v[38:39], v[66:67] op_sel_hi:[1,0]
	v_pk_mul_f32 v[36:37], v[40:41], v[66:67] op_sel_hi:[1,0]
	v_cvt_pk_bf16_f32 v34, v34, v35
	v_cvt_pk_bf16_f32 v35, v36, v37
	global_store_dwordx2 v[32:33], v[34:35], off offset:32
	v_pk_mul_f32 v[34:35], v[42:43], v[66:67] op_sel_hi:[1,0]
	v_pk_mul_f32 v[36:37], v[44:45], v[66:67] op_sel_hi:[1,0]
	v_cvt_pk_bf16_f32 v34, v34, v35
	v_cvt_pk_bf16_f32 v35, v36, v37
	global_store_dwordx2 v[32:33], v[34:35], off offset:64
	v_pk_mul_f32 v[34:35], v[46:47], v[66:67] op_sel_hi:[1,0]
	v_pk_mul_f32 v[36:37], v[48:49], v[66:67] op_sel_hi:[1,0]
	v_cvt_pk_bf16_f32 v34, v34, v35
	v_cvt_pk_bf16_f32 v35, v36, v37
	global_store_dwordx2 v[32:33], v[34:35], off offset:96
	v_pk_mul_f32 v[34:35], v[50:51], v[66:67] op_sel_hi:[1,0]
	v_pk_mul_f32 v[36:37], v[52:53], v[66:67] op_sel_hi:[1,0]
	v_cvt_pk_bf16_f32 v34, v34, v35
	v_cvt_pk_bf16_f32 v35, v36, v37
	global_store_dwordx2 v[32:33], v[34:35], off offset:128
	v_pk_mul_f32 v[34:35], v[54:55], v[66:67] op_sel_hi:[1,0]
	v_pk_mul_f32 v[36:37], v[56:57], v[66:67] op_sel_hi:[1,0]
	v_cvt_pk_bf16_f32 v34, v34, v35
	v_cvt_pk_bf16_f32 v35, v36, v37
	s_cmpk_lt_i32 s6, 0x400
	global_store_dwordx2 v[32:33], v[34:35], off offset:160
	v_pk_mul_f32 v[34:35], v[58:59], v[66:67] op_sel_hi:[1,0]
	v_pk_mul_f32 v[36:37], v[60:61], v[66:67] op_sel_hi:[1,0]
	s_cselect_b64 s[16:17], -1, 0
	s_cmp_lt_u32 s37, 63
	v_cvt_pk_bf16_f32 v34, v34, v35
	v_cvt_pk_bf16_f32 v35, v36, v37
	s_cselect_b64 s[24:25], -1, 0
	global_store_dwordx2 v[32:33], v[34:35], off offset:192
	v_pk_mul_f32 v[34:35], v[62:63], v[66:67] op_sel_hi:[1,0]
	v_pk_mul_f32 v[36:37], v[64:65], v[66:67] op_sel_hi:[1,0]
	v_pk_mul_f32 v[28:29], v[28:29], v[66:67] op_sel_hi:[1,0]
	v_pk_mul_f32 v[30:31], v[30:31], v[66:67] op_sel_hi:[1,0]
	v_pk_mul_f32 v[24:25], v[24:25], v[66:67] op_sel_hi:[1,0]
	v_pk_mul_f32 v[26:27], v[26:27], v[66:67] op_sel_hi:[1,0]
	v_pk_mul_f32 v[20:21], v[20:21], v[66:67] op_sel_hi:[1,0]
	v_pk_mul_f32 v[22:23], v[22:23], v[66:67] op_sel_hi:[1,0]
	v_pk_mul_f32 v[16:17], v[16:17], v[66:67] op_sel_hi:[1,0]
	v_pk_mul_f32 v[18:19], v[18:19], v[66:67] op_sel_hi:[1,0]
	v_pk_mul_f32 v[12:13], v[12:13], v[66:67] op_sel_hi:[1,0]
	v_pk_mul_f32 v[14:15], v[14:15], v[66:67] op_sel_hi:[1,0]
	v_pk_mul_f32 v[8:9], v[8:9], v[66:67] op_sel_hi:[1,0]
	v_pk_mul_f32 v[10:11], v[10:11], v[66:67] op_sel_hi:[1,0]
	v_pk_mul_f32 v[4:5], v[4:5], v[66:67] op_sel_hi:[1,0]
	v_pk_mul_f32 v[6:7], v[6:7], v[66:67] op_sel_hi:[1,0]
	v_pk_mul_f32 v[0:1], v[0:1], v[66:67] op_sel_hi:[1,0]
	v_pk_mul_f32 v[2:3], v[2:3], v[66:67] op_sel_hi:[1,0]
	s_and_b64 s[16:17], s[16:17], s[24:25]
	v_cvt_pk_bf16_f32 v34, v34, v35
	v_cvt_pk_bf16_f32 v35, v36, v37
	v_cvt_pk_bf16_f32 v28, v28, v29
	v_cvt_pk_bf16_f32 v29, v30, v31
	v_cvt_pk_bf16_f32 v24, v24, v25
	v_cvt_pk_bf16_f32 v25, v26, v27
	v_cvt_pk_bf16_f32 v20, v20, v21
	v_cvt_pk_bf16_f32 v21, v22, v23
	v_cvt_pk_bf16_f32 v16, v16, v17
	v_cvt_pk_bf16_f32 v17, v18, v19
	v_cvt_pk_bf16_f32 v12, v12, v13
	v_cvt_pk_bf16_f32 v13, v14, v15
	v_cvt_pk_bf16_f32 v8, v8, v9
	v_cvt_pk_bf16_f32 v9, v10, v11
	v_cvt_pk_bf16_f32 v4, v4, v5
	v_cvt_pk_bf16_f32 v5, v6, v7
	v_cvt_pk_bf16_f32 v0, v0, v1
	v_cvt_pk_bf16_f32 v1, v2, v3
	s_and_b64 vcc, exec, s[16:17]
	s_mov_b32 s37, s7
	global_store_dwordx2 v[32:33], v[34:35], off offset:224
	global_store_dwordx2 v[32:33], v[28:29], off offset:256
	global_store_dwordx2 v[32:33], v[24:25], off offset:288
	global_store_dwordx2 v[32:33], v[20:21], off offset:320
	global_store_dwordx2 v[32:33], v[16:17], off offset:352
	global_store_dwordx2 v[32:33], v[12:13], off offset:384
	global_store_dwordx2 v[32:33], v[8:9], off offset:416
	global_store_dwordx2 v[32:33], v[4:5], off offset:448
	global_store_dwordx2 v[32:33], v[0:1], off offset:480
	s_cbranch_vccnz .LBB0_1551
